# prologue transposes: 32 row loads in flight per item (was 8); forget-weight LDS setup: 16 loads in flight; on top of the norm-phase GEMV loop rewrite
# speedup vs baseline: 1.0002x; 1.0002x over previous
; __device__ __forceinline__ unsigned pk2(float lo, float hi) { unsigned r; asm volatile("v_cvt_pk_bf16_f32 %0, %1, %2" : "=v"(r) : "v"(lo), "v"(hi)); return r; }
; __device__ __forceinline__ void norm_phase(const float* src, const float* gain, const float* shp, const float* scp, bf16* XN,
;                                            const float* w_in, const float* b_f, float* LF, LAS unsigned char* lds, int tid, int lane, int wave, int gw, int ngw) {
;     ...
;     for (int idx = tid; idx < 8192; idx += NTHREADS) { const int k = idx >> 2, n4 = idx & 3;
;         const f32x4 v = *(const f32x4*)(w_in + (size_t)k * NIN + 3 * DM + 4 * n4);
; #pragma unroll
;         for (int i = 0; i < 4; ++i) { const unsigned hb = pk2(v[i], 0.f) & 0xffffu; const unsigned lb = pk2(v[i] - __uint_as_float(hb << 16), 0.f) & 0xffffu;
;             WFT[(4 * n4 + i) * WFT_LD + k] = (bf16)hb; WFT[(16 + 4 * n4 + i) * WFT_LD + k] = (bf16)lb; } }
.LBB0_559:
	v_ashrrev_i32_e32 v6, 2, v1
	v_mov_b64_e32 v[2:3], s[40:41]
	v_and_b32_e32 v7, 12, v0
	v_mad_i64_i32 v[2:3], s[20:21], v6, s91, v[2:3]
	v_lshlrev_b32_e32 v194, 2, v7
	v_lshl_add_u64 v[2:3], v[2:3], 0, v[194:195]
	v_add_co_u32_e32 v2, vcc, 0x6000, v2
	v_mul_u32_u24_e32 v7, 0x1010, v7
	s_nop 0
	v_addc_co_u32_e32 v3, vcc, 0, v3, vcc
	v_lshlrev_b32_e32 v6, 1, v6
	v_add3_u32 v6, 0, v7, v6
	v_add_u32_e32 v7, 0x10100, v6
	s_mov_b32 s18, 0x302000
	s_mov_b32 s19, 0
	global_load_dwordx4 v[32:35], v[2:3], off
	v_lshl_add_u64 v[2:3], v[2:3], 0, s[18:19]
	global_load_dwordx4 v[36:39], v[2:3], off
	v_lshl_add_u64 v[2:3], v[2:3], 0, s[18:19]
	global_load_dwordx4 v[40:43], v[2:3], off
	v_lshl_add_u64 v[2:3], v[2:3], 0, s[18:19]
	global_load_dwordx4 v[44:47], v[2:3], off
	v_lshl_add_u64 v[2:3], v[2:3], 0, s[18:19]
	global_load_dwordx4 v[48:51], v[2:3], off
	v_lshl_add_u64 v[2:3], v[2:3], 0, s[18:19]
	global_load_dwordx4 v[52:55], v[2:3], off
	v_lshl_add_u64 v[2:3], v[2:3], 0, s[18:19]
	global_load_dwordx4 v[56:59], v[2:3], off
	v_lshl_add_u64 v[2:3], v[2:3], 0, s[18:19]
	global_load_dwordx4 v[60:63], v[2:3], off
	v_lshl_add_u64 v[2:3], v[2:3], 0, s[18:19]
	global_load_dwordx4 v[64:67], v[2:3], off
	v_lshl_add_u64 v[2:3], v[2:3], 0, s[18:19]
	global_load_dwordx4 v[68:71], v[2:3], off
	v_lshl_add_u64 v[2:3], v[2:3], 0, s[18:19]
	global_load_dwordx4 v[72:75], v[2:3], off
	v_lshl_add_u64 v[2:3], v[2:3], 0, s[18:19]
	global_load_dwordx4 v[76:79], v[2:3], off
	v_lshl_add_u64 v[2:3], v[2:3], 0, s[18:19]
	global_load_dwordx4 v[80:83], v[2:3], off
	v_lshl_add_u64 v[2:3], v[2:3], 0, s[18:19]
	global_load_dwordx4 v[84:87], v[2:3], off
	v_lshl_add_u64 v[2:3], v[2:3], 0, s[18:19]
	global_load_dwordx4 v[88:91], v[2:3], off
	v_lshl_add_u64 v[2:3], v[2:3], 0, s[18:19]
	global_load_dwordx4 v[92:95], v[2:3], off
	s_waitcnt vmcnt(15)
	v_cvt_pk_bf16_f32 v11, v32, v195
	s_nop 0
	v_lshlrev_b32_e32 v12, 16, v11
	v_sub_f32_e32 v32, v32, v12
	v_cvt_pk_bf16_f32 v32, v32, v195
	s_nop 0
	ds_write_b16 v6, v11
	ds_write_b16 v7, v32
	v_cvt_pk_bf16_f32 v11, v33, v195
	s_nop 0
	v_lshlrev_b32_e32 v12, 16, v11
	v_sub_f32_e32 v33, v33, v12
	v_cvt_pk_bf16_f32 v33, v33, v195
	s_nop 0
	ds_write_b16 v6, v11 offset:4112
	ds_write_b16 v7, v33 offset:4112
	v_cvt_pk_bf16_f32 v11, v34, v195
	s_nop 0
	v_lshlrev_b32_e32 v12, 16, v11
	v_sub_f32_e32 v34, v34, v12
	v_cvt_pk_bf16_f32 v34, v34, v195
	s_nop 0
	ds_write_b16 v6, v11 offset:8224
	ds_write_b16 v7, v34 offset:8224
	v_cvt_pk_bf16_f32 v11, v35, v195
	s_nop 0
	v_lshlrev_b32_e32 v12, 16, v11
	v_sub_f32_e32 v35, v35, v12
	v_cvt_pk_bf16_f32 v35, v35, v195
	s_nop 0
	ds_write_b16 v6, v11 offset:12336
	ds_write_b16 v7, v35 offset:12336
	s_waitcnt vmcnt(14)
	v_cvt_pk_bf16_f32 v11, v36, v195
	s_nop 0
	v_lshlrev_b32_e32 v12, 16, v11
	v_sub_f32_e32 v36, v36, v12
	v_cvt_pk_bf16_f32 v36, v36, v195
	s_nop 0
	ds_write_b16 v6, v11 offset:256
	ds_write_b16 v7, v36 offset:256
	v_cvt_pk_bf16_f32 v11, v37, v195
	s_nop 0
	v_lshlrev_b32_e32 v12, 16, v11
	v_sub_f32_e32 v37, v37, v12
	v_cvt_pk_bf16_f32 v37, v37, v195
	s_nop 0
	ds_write_b16 v6, v11 offset:4368
	ds_write_b16 v7, v37 offset:4368
	v_cvt_pk_bf16_f32 v11, v38, v195
	s_nop 0
	v_lshlrev_b32_e32 v12, 16, v11
	v_sub_f32_e32 v38, v38, v12
	v_cvt_pk_bf16_f32 v38, v38, v195
	s_nop 0
	ds_write_b16 v6, v11 offset:8480
	ds_write_b16 v7, v38 offset:8480
	v_cvt_pk_bf16_f32 v11, v39, v195
	s_nop 0
	v_lshlrev_b32_e32 v12, 16, v11
	v_sub_f32_e32 v39, v39, v12
	v_cvt_pk_bf16_f32 v39, v39, v195
	s_nop 0
	ds_write_b16 v6, v11 offset:12592
	ds_write_b16 v7, v39 offset:12592
	s_waitcnt vmcnt(13)
	v_cvt_pk_bf16_f32 v11, v40, v195
	s_nop 0
	v_lshlrev_b32_e32 v12, 16, v11
	v_sub_f32_e32 v40, v40, v12
	v_cvt_pk_bf16_f32 v40, v40, v195
	s_nop 0
	ds_write_b16 v6, v11 offset:512
	ds_write_b16 v7, v40 offset:512
	v_cvt_pk_bf16_f32 v11, v41, v195
	s_nop 0
	v_lshlrev_b32_e32 v12, 16, v11
	v_sub_f32_e32 v41, v41, v12
	v_cvt_pk_bf16_f32 v41, v41, v195
	s_nop 0
	ds_write_b16 v6, v11 offset:4624
	ds_write_b16 v7, v41 offset:4624
	v_cvt_pk_bf16_f32 v11, v42, v195
	s_nop 0
	v_lshlrev_b32_e32 v12, 16, v11
	v_sub_f32_e32 v42, v42, v12
	v_cvt_pk_bf16_f32 v42, v42, v195
	s_nop 0
	ds_write_b16 v6, v11 offset:8736
	ds_write_b16 v7, v42 offset:8736
	v_cvt_pk_bf16_f32 v11, v43, v195
	s_nop 0
	v_lshlrev_b32_e32 v12, 16, v11
	v_sub_f32_e32 v43, v43, v12
	v_cvt_pk_bf16_f32 v43, v43, v195
	s_nop 0
	ds_write_b16 v6, v11 offset:12848
	ds_write_b16 v7, v43 offset:12848
	s_waitcnt vmcnt(12)
	v_cvt_pk_bf16_f32 v11, v44, v195
	s_nop 0
	v_lshlrev_b32_e32 v12, 16, v11
	v_sub_f32_e32 v44, v44, v12
	v_cvt_pk_bf16_f32 v44, v44, v195
	s_nop 0
	ds_write_b16 v6, v11 offset:768
	ds_write_b16 v7, v44 offset:768
	v_cvt_pk_bf16_f32 v11, v45, v195
	s_nop 0
	v_lshlrev_b32_e32 v12, 16, v11
	v_sub_f32_e32 v45, v45, v12
	v_cvt_pk_bf16_f32 v45, v45, v195
	s_nop 0
	ds_write_b16 v6, v11 offset:4880
	ds_write_b16 v7, v45 offset:4880
	v_cvt_pk_bf16_f32 v11, v46, v195
	s_nop 0
	v_lshlrev_b32_e32 v12, 16, v11
	v_sub_f32_e32 v46, v46, v12
	v_cvt_pk_bf16_f32 v46, v46, v195
	s_nop 0
	ds_write_b16 v6, v11 offset:8992
	ds_write_b16 v7, v46 offset:8992
	v_cvt_pk_bf16_f32 v11, v47, v195
	s_nop 0
	v_lshlrev_b32_e32 v12, 16, v11
	v_sub_f32_e32 v47, v47, v12
	v_cvt_pk_bf16_f32 v47, v47, v195
	s_nop 0
	ds_write_b16 v6, v11 offset:13104
	ds_write_b16 v7, v47 offset:13104
	s_waitcnt vmcnt(11)
; __device__ __forceinline__ unsigned pk2(float lo, float hi) { unsigned r; asm volatile("v_cvt_pk_bf16_f32 %0, %1, %2" : "=v"(r) : "v"(lo), "v"(hi)); return r; }
; __device__ __forceinline__ void norm_phase(const float* src, const float* gain, const float* shp, const float* scp, bf16* XN,
;                                            const float* w_in, const float* b_f, float* LF, LAS unsigned char* lds, int tid, int lane, int wave, int gw, int ngw) {
;     ...
;     for (int idx = tid; idx < 8192; idx += NTHREADS) { const int k = idx >> 2, n4 = idx & 3;
;         const f32x4 v = *(const f32x4*)(w_in + (size_t)k * NIN + 3 * DM + 4 * n4);
; #pragma unroll
;         for (int i = 0; i < 4; ++i) { const unsigned hb = pk2(v[i], 0.f) & 0xffffu; const unsigned lb = pk2(v[i] - __uint_as_float(hb << 16), 0.f) & 0xffffu;
;             WFT[(4 * n4 + i) * WFT_LD + k] = (bf16)hb; WFT[(16 + 4 * n4 + i) * WFT_LD + k] = (bf16)lb; } }
	v_cvt_pk_bf16_f32 v11, v48, v195
	s_nop 0
	v_lshlrev_b32_e32 v12, 16, v11
	v_sub_f32_e32 v48, v48, v12
	v_cvt_pk_bf16_f32 v48, v48, v195
	s_nop 0
	ds_write_b16 v6, v11 offset:1024
	ds_write_b16 v7, v48 offset:1024
	v_cvt_pk_bf16_f32 v11, v49, v195
	s_nop 0
	v_lshlrev_b32_e32 v12, 16, v11
	v_sub_f32_e32 v49, v49, v12
	v_cvt_pk_bf16_f32 v49, v49, v195
	s_nop 0
	ds_write_b16 v6, v11 offset:5136
	ds_write_b16 v7, v49 offset:5136
	v_cvt_pk_bf16_f32 v11, v50, v195
	s_nop 0
	v_lshlrev_b32_e32 v12, 16, v11
	v_sub_f32_e32 v50, v50, v12
	v_cvt_pk_bf16_f32 v50, v50, v195
	s_nop 0
	ds_write_b16 v6, v11 offset:9248
	ds_write_b16 v7, v50 offset:9248
	v_cvt_pk_bf16_f32 v11, v51, v195
	s_nop 0
	v_lshlrev_b32_e32 v12, 16, v11
	v_sub_f32_e32 v51, v51, v12
	v_cvt_pk_bf16_f32 v51, v51, v195
	s_nop 0
	ds_write_b16 v6, v11 offset:13360
	ds_write_b16 v7, v51 offset:13360
	s_waitcnt vmcnt(10)
	v_cvt_pk_bf16_f32 v11, v52, v195
	s_nop 0
	v_lshlrev_b32_e32 v12, 16, v11
	v_sub_f32_e32 v52, v52, v12
	v_cvt_pk_bf16_f32 v52, v52, v195
	s_nop 0
	ds_write_b16 v6, v11 offset:1280
	ds_write_b16 v7, v52 offset:1280
	v_cvt_pk_bf16_f32 v11, v53, v195
	s_nop 0
	v_lshlrev_b32_e32 v12, 16, v11
	v_sub_f32_e32 v53, v53, v12
	v_cvt_pk_bf16_f32 v53, v53, v195
	s_nop 0
	ds_write_b16 v6, v11 offset:5392
	ds_write_b16 v7, v53 offset:5392
	v_cvt_pk_bf16_f32 v11, v54, v195
	s_nop 0
	v_lshlrev_b32_e32 v12, 16, v11
	v_sub_f32_e32 v54, v54, v12
	v_cvt_pk_bf16_f32 v54, v54, v195
	s_nop 0
	ds_write_b16 v6, v11 offset:9504
	ds_write_b16 v7, v54 offset:9504
	v_cvt_pk_bf16_f32 v11, v55, v195
	s_nop 0
	v_lshlrev_b32_e32 v12, 16, v11
	v_sub_f32_e32 v55, v55, v12
	v_cvt_pk_bf16_f32 v55, v55, v195
	s_nop 0
	ds_write_b16 v6, v11 offset:13616
	ds_write_b16 v7, v55 offset:13616
	s_waitcnt vmcnt(9)
	v_cvt_pk_bf16_f32 v11, v56, v195
	s_nop 0
	v_lshlrev_b32_e32 v12, 16, v11
	v_sub_f32_e32 v56, v56, v12
	v_cvt_pk_bf16_f32 v56, v56, v195
	s_nop 0
	ds_write_b16 v6, v11 offset:1536
	ds_write_b16 v7, v56 offset:1536
	v_cvt_pk_bf16_f32 v11, v57, v195
	s_nop 0
	v_lshlrev_b32_e32 v12, 16, v11
	v_sub_f32_e32 v57, v57, v12
	v_cvt_pk_bf16_f32 v57, v57, v195
	s_nop 0
	ds_write_b16 v6, v11 offset:5648
	ds_write_b16 v7, v57 offset:5648
	v_cvt_pk_bf16_f32 v11, v58, v195
	s_nop 0
	v_lshlrev_b32_e32 v12, 16, v11
	v_sub_f32_e32 v58, v58, v12
	v_cvt_pk_bf16_f32 v58, v58, v195
	s_nop 0
	ds_write_b16 v6, v11 offset:9760
	ds_write_b16 v7, v58 offset:9760
	v_cvt_pk_bf16_f32 v11, v59, v195
	s_nop 0
	v_lshlrev_b32_e32 v12, 16, v11
	v_sub_f32_e32 v59, v59, v12
	v_cvt_pk_bf16_f32 v59, v59, v195
	s_nop 0
	ds_write_b16 v6, v11 offset:13872
	ds_write_b16 v7, v59 offset:13872
	s_waitcnt vmcnt(8)
	v_cvt_pk_bf16_f32 v11, v60, v195
	s_nop 0
	v_lshlrev_b32_e32 v12, 16, v11
	v_sub_f32_e32 v60, v60, v12
	v_cvt_pk_bf16_f32 v60, v60, v195
	s_nop 0
	ds_write_b16 v6, v11 offset:1792
	ds_write_b16 v7, v60 offset:1792
	v_cvt_pk_bf16_f32 v11, v61, v195
	s_nop 0
	v_lshlrev_b32_e32 v12, 16, v11
	v_sub_f32_e32 v61, v61, v12
	v_cvt_pk_bf16_f32 v61, v61, v195
	s_nop 0
	ds_write_b16 v6, v11 offset:5904
	ds_write_b16 v7, v61 offset:5904
	v_cvt_pk_bf16_f32 v11, v62, v195
	s_nop 0
	v_lshlrev_b32_e32 v12, 16, v11
	v_sub_f32_e32 v62, v62, v12
	v_cvt_pk_bf16_f32 v62, v62, v195
	s_nop 0
	ds_write_b16 v6, v11 offset:10016
	ds_write_b16 v7, v62 offset:10016
	v_cvt_pk_bf16_f32 v11, v63, v195
	s_nop 0
	v_lshlrev_b32_e32 v12, 16, v11
	v_sub_f32_e32 v63, v63, v12
	v_cvt_pk_bf16_f32 v63, v63, v195
	s_nop 0
	ds_write_b16 v6, v11 offset:14128
	ds_write_b16 v7, v63 offset:14128
	s_waitcnt vmcnt(7)
	v_cvt_pk_bf16_f32 v11, v64, v195
	s_nop 0
	v_lshlrev_b32_e32 v12, 16, v11
	v_sub_f32_e32 v64, v64, v12
	v_cvt_pk_bf16_f32 v64, v64, v195
	s_nop 0
	ds_write_b16 v6, v11 offset:2048
	ds_write_b16 v7, v64 offset:2048
	v_cvt_pk_bf16_f32 v11, v65, v195
	s_nop 0
	v_lshlrev_b32_e32 v12, 16, v11
	v_sub_f32_e32 v65, v65, v12
	v_cvt_pk_bf16_f32 v65, v65, v195
	s_nop 0
	ds_write_b16 v6, v11 offset:6160
	ds_write_b16 v7, v65 offset:6160
	v_cvt_pk_bf16_f32 v11, v66, v195
	s_nop 0
	v_lshlrev_b32_e32 v12, 16, v11
	v_sub_f32_e32 v66, v66, v12
	v_cvt_pk_bf16_f32 v66, v66, v195
	s_nop 0
	ds_write_b16 v6, v11 offset:10272
	ds_write_b16 v7, v66 offset:10272
	v_cvt_pk_bf16_f32 v11, v67, v195
	s_nop 0
	v_lshlrev_b32_e32 v12, 16, v11
	v_sub_f32_e32 v67, v67, v12
	v_cvt_pk_bf16_f32 v67, v67, v195
	s_nop 0
	ds_write_b16 v6, v11 offset:14384
	ds_write_b16 v7, v67 offset:14384
	s_waitcnt vmcnt(6)
	v_cvt_pk_bf16_f32 v11, v68, v195
	s_nop 0
	v_lshlrev_b32_e32 v12, 16, v11
	v_sub_f32_e32 v68, v68, v12
	v_cvt_pk_bf16_f32 v68, v68, v195
	s_nop 0
	ds_write_b16 v6, v11 offset:2304
	ds_write_b16 v7, v68 offset:2304
	v_cvt_pk_bf16_f32 v11, v69, v195
	s_nop 0
	v_lshlrev_b32_e32 v12, 16, v11
	v_sub_f32_e32 v69, v69, v12
	v_cvt_pk_bf16_f32 v69, v69, v195
	s_nop 0
	ds_write_b16 v6, v11 offset:6416
	ds_write_b16 v7, v69 offset:6416
	v_cvt_pk_bf16_f32 v11, v70, v195
	s_nop 0
	v_lshlrev_b32_e32 v12, 16, v11
	v_sub_f32_e32 v70, v70, v12
	v_cvt_pk_bf16_f32 v70, v70, v195
	s_nop 0
	ds_write_b16 v6, v11 offset:10528
	ds_write_b16 v7, v70 offset:10528
	v_cvt_pk_bf16_f32 v11, v71, v195
	s_nop 0
	v_lshlrev_b32_e32 v12, 16, v11
	v_sub_f32_e32 v71, v71, v12
	v_cvt_pk_bf16_f32 v71, v71, v195
	s_nop 0
	ds_write_b16 v6, v11 offset:14640
	ds_write_b16 v7, v71 offset:14640
	s_waitcnt vmcnt(5)
; __device__ __forceinline__ unsigned pk2(float lo, float hi) { unsigned r; asm volatile("v_cvt_pk_bf16_f32 %0, %1, %2" : "=v"(r) : "v"(lo), "v"(hi)); return r; }
; __device__ __forceinline__ void norm_phase(const float* src, const float* gain, const float* shp, const float* scp, bf16* XN,
;                                            const float* w_in, const float* b_f, float* LF, LAS unsigned char* lds, int tid, int lane, int wave, int gw, int ngw) {
;     ...
;     for (int idx = tid; idx < 8192; idx += NTHREADS) { const int k = idx >> 2, n4 = idx & 3;
;         const f32x4 v = *(const f32x4*)(w_in + (size_t)k * NIN + 3 * DM + 4 * n4);
; #pragma unroll
;         for (int i = 0; i < 4; ++i) { const unsigned hb = pk2(v[i], 0.f) & 0xffffu; const unsigned lb = pk2(v[i] - __uint_as_float(hb << 16), 0.f) & 0xffffu;
;             WFT[(4 * n4 + i) * WFT_LD + k] = (bf16)hb; WFT[(16 + 4 * n4 + i) * WFT_LD + k] = (bf16)lb; } }
	v_cvt_pk_bf16_f32 v11, v72, v195
	s_nop 0
	v_lshlrev_b32_e32 v12, 16, v11
	v_sub_f32_e32 v72, v72, v12
	v_cvt_pk_bf16_f32 v72, v72, v195
	s_nop 0
	ds_write_b16 v6, v11 offset:2560
	ds_write_b16 v7, v72 offset:2560
	v_cvt_pk_bf16_f32 v11, v73, v195
	s_nop 0
	v_lshlrev_b32_e32 v12, 16, v11
	v_sub_f32_e32 v73, v73, v12
	v_cvt_pk_bf16_f32 v73, v73, v195
	s_nop 0
	ds_write_b16 v6, v11 offset:6672
	ds_write_b16 v7, v73 offset:6672
	v_cvt_pk_bf16_f32 v11, v74, v195
	s_nop 0
	v_lshlrev_b32_e32 v12, 16, v11
	v_sub_f32_e32 v74, v74, v12
	v_cvt_pk_bf16_f32 v74, v74, v195
	s_nop 0
	ds_write_b16 v6, v11 offset:10784
	ds_write_b16 v7, v74 offset:10784
	v_cvt_pk_bf16_f32 v11, v75, v195
	s_nop 0
	v_lshlrev_b32_e32 v12, 16, v11
	v_sub_f32_e32 v75, v75, v12
	v_cvt_pk_bf16_f32 v75, v75, v195
	s_nop 0
	ds_write_b16 v6, v11 offset:14896
	ds_write_b16 v7, v75 offset:14896
	s_waitcnt vmcnt(4)
	v_cvt_pk_bf16_f32 v11, v76, v195
	s_nop 0
	v_lshlrev_b32_e32 v12, 16, v11
	v_sub_f32_e32 v76, v76, v12
	v_cvt_pk_bf16_f32 v76, v76, v195
	s_nop 0
	ds_write_b16 v6, v11 offset:2816
	ds_write_b16 v7, v76 offset:2816
	v_cvt_pk_bf16_f32 v11, v77, v195
	s_nop 0
	v_lshlrev_b32_e32 v12, 16, v11
	v_sub_f32_e32 v77, v77, v12
	v_cvt_pk_bf16_f32 v77, v77, v195
	s_nop 0
	ds_write_b16 v6, v11 offset:6928
	ds_write_b16 v7, v77 offset:6928
	v_cvt_pk_bf16_f32 v11, v78, v195
	s_nop 0
	v_lshlrev_b32_e32 v12, 16, v11
	v_sub_f32_e32 v78, v78, v12
	v_cvt_pk_bf16_f32 v78, v78, v195
	s_nop 0
	ds_write_b16 v6, v11 offset:11040
	ds_write_b16 v7, v78 offset:11040
	v_cvt_pk_bf16_f32 v11, v79, v195
	s_nop 0
	v_lshlrev_b32_e32 v12, 16, v11
	v_sub_f32_e32 v79, v79, v12
	v_cvt_pk_bf16_f32 v79, v79, v195
	s_nop 0
	ds_write_b16 v6, v11 offset:15152
	ds_write_b16 v7, v79 offset:15152
	s_waitcnt vmcnt(3)
	v_cvt_pk_bf16_f32 v11, v80, v195
	s_nop 0
	v_lshlrev_b32_e32 v12, 16, v11
	v_sub_f32_e32 v80, v80, v12
	v_cvt_pk_bf16_f32 v80, v80, v195
	s_nop 0
	ds_write_b16 v6, v11 offset:3072
	ds_write_b16 v7, v80 offset:3072
	v_cvt_pk_bf16_f32 v11, v81, v195
	s_nop 0
	v_lshlrev_b32_e32 v12, 16, v11
	v_sub_f32_e32 v81, v81, v12
	v_cvt_pk_bf16_f32 v81, v81, v195
	s_nop 0
	ds_write_b16 v6, v11 offset:7184
	ds_write_b16 v7, v81 offset:7184
	v_cvt_pk_bf16_f32 v11, v82, v195
	s_nop 0
	v_lshlrev_b32_e32 v12, 16, v11
	v_sub_f32_e32 v82, v82, v12
	v_cvt_pk_bf16_f32 v82, v82, v195
	s_nop 0
	ds_write_b16 v6, v11 offset:11296
	ds_write_b16 v7, v82 offset:11296
	v_cvt_pk_bf16_f32 v11, v83, v195
	s_nop 0
	v_lshlrev_b32_e32 v12, 16, v11
	v_sub_f32_e32 v83, v83, v12
	v_cvt_pk_bf16_f32 v83, v83, v195
	s_nop 0
	ds_write_b16 v6, v11 offset:15408
	ds_write_b16 v7, v83 offset:15408
	s_waitcnt vmcnt(2)
	v_cvt_pk_bf16_f32 v11, v84, v195
	s_nop 0
	v_lshlrev_b32_e32 v12, 16, v11
	v_sub_f32_e32 v84, v84, v12
	v_cvt_pk_bf16_f32 v84, v84, v195
	s_nop 0
	ds_write_b16 v6, v11 offset:3328
	ds_write_b16 v7, v84 offset:3328
	v_cvt_pk_bf16_f32 v11, v85, v195
	s_nop 0
	v_lshlrev_b32_e32 v12, 16, v11
	v_sub_f32_e32 v85, v85, v12
	v_cvt_pk_bf16_f32 v85, v85, v195
	s_nop 0
	ds_write_b16 v6, v11 offset:7440
	ds_write_b16 v7, v85 offset:7440
	v_cvt_pk_bf16_f32 v11, v86, v195
	s_nop 0
	v_lshlrev_b32_e32 v12, 16, v11
	v_sub_f32_e32 v86, v86, v12
	v_cvt_pk_bf16_f32 v86, v86, v195
	s_nop 0
	ds_write_b16 v6, v11 offset:11552
	ds_write_b16 v7, v86 offset:11552
	v_cvt_pk_bf16_f32 v11, v87, v195
	s_nop 0
	v_lshlrev_b32_e32 v12, 16, v11
	v_sub_f32_e32 v87, v87, v12
	v_cvt_pk_bf16_f32 v87, v87, v195
	s_nop 0
	ds_write_b16 v6, v11 offset:15664
	ds_write_b16 v7, v87 offset:15664
	s_waitcnt vmcnt(1)
	v_cvt_pk_bf16_f32 v11, v88, v195
	s_nop 0
	v_lshlrev_b32_e32 v12, 16, v11
	v_sub_f32_e32 v88, v88, v12
	v_cvt_pk_bf16_f32 v88, v88, v195
	s_nop 0
	ds_write_b16 v6, v11 offset:3584
	ds_write_b16 v7, v88 offset:3584
	v_cvt_pk_bf16_f32 v11, v89, v195
	s_nop 0
	v_lshlrev_b32_e32 v12, 16, v11
	v_sub_f32_e32 v89, v89, v12
	v_cvt_pk_bf16_f32 v89, v89, v195
	s_nop 0
	ds_write_b16 v6, v11 offset:7696
	ds_write_b16 v7, v89 offset:7696
	v_cvt_pk_bf16_f32 v11, v90, v195
	s_nop 0
	v_lshlrev_b32_e32 v12, 16, v11
	v_sub_f32_e32 v90, v90, v12
	v_cvt_pk_bf16_f32 v90, v90, v195
	s_nop 0
	ds_write_b16 v6, v11 offset:11808
	ds_write_b16 v7, v90 offset:11808
	v_cvt_pk_bf16_f32 v11, v91, v195
	s_nop 0
	v_lshlrev_b32_e32 v12, 16, v11
	v_sub_f32_e32 v91, v91, v12
	v_cvt_pk_bf16_f32 v91, v91, v195
	s_nop 0
	ds_write_b16 v6, v11 offset:15920
	ds_write_b16 v7, v91 offset:15920
	s_waitcnt vmcnt(0)
	v_cvt_pk_bf16_f32 v11, v92, v195
	s_nop 0
	v_lshlrev_b32_e32 v12, 16, v11
	v_sub_f32_e32 v92, v92, v12
	v_cvt_pk_bf16_f32 v92, v92, v195
	s_nop 0
	ds_write_b16 v6, v11 offset:3840
	ds_write_b16 v7, v92 offset:3840
	v_cvt_pk_bf16_f32 v11, v93, v195
	s_nop 0
	v_lshlrev_b32_e32 v12, 16, v11
	v_sub_f32_e32 v93, v93, v12
	v_cvt_pk_bf16_f32 v93, v93, v195
	s_nop 0
	ds_write_b16 v6, v11 offset:7952
	ds_write_b16 v7, v93 offset:7952
	v_cvt_pk_bf16_f32 v11, v94, v195
	s_nop 0
	v_lshlrev_b32_e32 v12, 16, v11
	v_sub_f32_e32 v94, v94, v12
	v_cvt_pk_bf16_f32 v94, v94, v195
	s_nop 0
	ds_write_b16 v6, v11 offset:12064
	ds_write_b16 v7, v94 offset:12064
	v_cvt_pk_bf16_f32 v11, v95, v195
	s_nop 0
	v_lshlrev_b32_e32 v12, 16, v11
	v_sub_f32_e32 v95, v95, v12
	v_cvt_pk_bf16_f32 v95, v95, v195
	s_nop 0
	ds_write_b16 v6, v11 offset:16176
	ds_write_b16 v7, v95 offset:16176

; __device__ __forceinline__ void p0_transpose_item(const float* W, int ld, int K, int nblk, bf16* WT, LAS float* scr, int item, int lane, bool cumap = false) {
;     ...
; #pragma unroll 8
;     for (int i = 0; i < 32; ++i) { const int kk = 2 * i + (lane >> 5); scr[kk * 33 + (lane & 31)] = __builtin_nontemporal_load(W + (size_t)(k0 + kk) * ld + n0 + (lane & 31)); }
.LBB0_596:
	v_lshl_add_u64 v[128:129], v[34:35], 0, s[10:11]
	v_lshl_add_u64 v[130:131], v[32:33], 0, s[10:11]
	v_lshl_add_u64 v[132:133], v[30:31], 0, s[10:11]
	v_lshl_add_u64 v[134:135], v[28:29], 0, s[10:11]
	v_lshl_add_u64 v[136:137], v[26:27], 0, s[10:11]
	v_lshl_add_u64 v[138:139], v[24:25], 0, s[10:11]
	v_lshl_add_u64 v[140:141], v[22:23], 0, s[10:11]
	v_lshl_add_u64 v[142:143], v[20:21], 0, s[10:11]
	global_load_dword v96, v[128:129], off nt
	global_load_dword v97, v[130:131], off nt
	global_load_dword v98, v[132:133], off nt
	global_load_dword v99, v[134:135], off nt
	global_load_dword v100, v[136:137], off nt
	global_load_dword v101, v[138:139], off nt
	global_load_dword v102, v[140:141], off nt
	global_load_dword v103, v[142:143], off nt
	s_add_u32 s10, s10, 0x20000
	s_addc_u32 s11, s11, 0
	v_lshl_add_u64 v[128:129], v[34:35], 0, s[10:11]
	v_lshl_add_u64 v[130:131], v[32:33], 0, s[10:11]
	v_lshl_add_u64 v[132:133], v[30:31], 0, s[10:11]
	v_lshl_add_u64 v[134:135], v[28:29], 0, s[10:11]
	v_lshl_add_u64 v[136:137], v[26:27], 0, s[10:11]
	v_lshl_add_u64 v[138:139], v[24:25], 0, s[10:11]
	v_lshl_add_u64 v[140:141], v[22:23], 0, s[10:11]
	v_lshl_add_u64 v[142:143], v[20:21], 0, s[10:11]
	global_load_dword v104, v[128:129], off nt
	global_load_dword v105, v[130:131], off nt
	global_load_dword v106, v[132:133], off nt
	global_load_dword v107, v[134:135], off nt
	global_load_dword v108, v[136:137], off nt
	global_load_dword v109, v[138:139], off nt
	global_load_dword v110, v[140:141], off nt
	global_load_dword v111, v[142:143], off nt
	s_add_u32 s10, s10, 0x20000
	s_addc_u32 s11, s11, 0
	v_lshl_add_u64 v[128:129], v[34:35], 0, s[10:11]
	v_lshl_add_u64 v[130:131], v[32:33], 0, s[10:11]
	v_lshl_add_u64 v[132:133], v[30:31], 0, s[10:11]
	v_lshl_add_u64 v[134:135], v[28:29], 0, s[10:11]
	v_lshl_add_u64 v[136:137], v[26:27], 0, s[10:11]
	v_lshl_add_u64 v[138:139], v[24:25], 0, s[10:11]
	v_lshl_add_u64 v[140:141], v[22:23], 0, s[10:11]
	v_lshl_add_u64 v[142:143], v[20:21], 0, s[10:11]
	global_load_dword v112, v[128:129], off nt
	global_load_dword v113, v[130:131], off nt
	global_load_dword v114, v[132:133], off nt
	global_load_dword v115, v[134:135], off nt
	global_load_dword v116, v[136:137], off nt
	global_load_dword v117, v[138:139], off nt
	global_load_dword v118, v[140:141], off nt
	global_load_dword v119, v[142:143], off nt
	s_add_u32 s10, s10, 0x20000
	s_addc_u32 s11, s11, 0
	v_lshl_add_u64 v[128:129], v[34:35], 0, s[10:11]
	v_lshl_add_u64 v[130:131], v[32:33], 0, s[10:11]
	v_lshl_add_u64 v[132:133], v[30:31], 0, s[10:11]
	v_lshl_add_u64 v[134:135], v[28:29], 0, s[10:11]
	v_lshl_add_u64 v[136:137], v[26:27], 0, s[10:11]
	v_lshl_add_u64 v[138:139], v[24:25], 0, s[10:11]
	v_lshl_add_u64 v[140:141], v[22:23], 0, s[10:11]
	v_lshl_add_u64 v[142:143], v[20:21], 0, s[10:11]
	global_load_dword v120, v[128:129], off nt
	global_load_dword v121, v[130:131], off nt
	global_load_dword v122, v[132:133], off nt
	global_load_dword v123, v[134:135], off nt
	global_load_dword v124, v[136:137], off nt
	global_load_dword v125, v[138:139], off nt
	global_load_dword v126, v[140:141], off nt
	global_load_dword v127, v[142:143], off nt
	s_add_u32 s10, s10, 0x20000
	s_addc_u32 s11, s11, 0
	v_add_u32_e32 v67, 0x400, v58
	s_waitcnt vmcnt(30)
	ds_write2_b32 v58, v96, v97 offset1:66
	s_waitcnt vmcnt(28)
	ds_write2_b32 v58, v98, v99 offset0:132 offset1:198
	s_waitcnt vmcnt(26)
	ds_write2_b32 v67, v100, v101 offset0:8 offset1:74
	s_waitcnt vmcnt(24)
	ds_write2_b32 v67, v102, v103 offset0:140 offset1:206
	v_add_u32_e32 v58, 0x840, v58
	v_add_u32_e32 v67, 0x400, v58
	s_waitcnt vmcnt(22)
; #define LAS __attribute__((address_space(3)))
; #define LDS_WAIT() asm volatile("s_waitcnt lgkmcnt(0)" ::: "memory")
; __device__ __forceinline__ unsigned pk2(float lo, float hi) { unsigned r; asm volatile("v_cvt_pk_bf16_f32 %0, %1, %2" : "=v"(r) : "v"(lo), "v"(hi)); return r; }
; __device__ __forceinline__ void p0_transpose_item(const float* W, int ld, int K, int nblk, bf16* WT, LAS float* scr, int item, int lane, bool cumap = false) {
;     ...
;     for (int i = 0; i < 32; ++i) { const int kk = 2 * i + (lane >> 5); scr[kk * 33 + (lane & 31)] = __builtin_nontemporal_load(W + (size_t)(k0 + kk) * ld + n0 + (lane & 31)); }
;     LDS_WAIT(); asm volatile("" ::: "memory");
;     const int c = lane & 7;
; #pragma unroll
;     for (int j = 0; j < 4; ++j) { const int n = (lane >> 3) + 8 * j; const LAS float* s = scr + (8 * c) * 33 + n;
;         v4u o; o.x = pk2(s[0 * 33], s[1 * 33]); o.y = pk2(s[2 * 33], s[3 * 33]); o.z = pk2(s[4 * 33], s[5 * 33]); o.w = pk2(s[6 * 33], s[7 * 33]);
;         *(v4u*)(WT + (size_t)(d0 + n) * K + k0 + 8 * c) = o; }
;     LDS_WAIT(); asm volatile("" ::: "memory");
	ds_write2_b32 v58, v104, v105 offset1:66
	s_waitcnt vmcnt(20)
	ds_write2_b32 v58, v106, v107 offset0:132 offset1:198
	s_waitcnt vmcnt(18)
	ds_write2_b32 v67, v108, v109 offset0:8 offset1:74
	s_waitcnt vmcnt(16)
	ds_write2_b32 v67, v110, v111 offset0:140 offset1:206
	v_add_u32_e32 v58, 0x840, v58
	v_add_u32_e32 v67, 0x400, v58
	s_waitcnt vmcnt(14)
	ds_write2_b32 v58, v112, v113 offset1:66
	s_waitcnt vmcnt(12)
	ds_write2_b32 v58, v114, v115 offset0:132 offset1:198
	s_waitcnt vmcnt(10)
	ds_write2_b32 v67, v116, v117 offset0:8 offset1:74
	s_waitcnt vmcnt(8)
	ds_write2_b32 v67, v118, v119 offset0:140 offset1:206
	v_add_u32_e32 v58, 0x840, v58
	v_add_u32_e32 v67, 0x400, v58
	s_waitcnt vmcnt(6)
	ds_write2_b32 v58, v120, v121 offset1:66
	s_waitcnt vmcnt(4)
	ds_write2_b32 v58, v122, v123 offset0:132 offset1:198
	s_waitcnt vmcnt(2)
	ds_write2_b32 v67, v124, v125 offset0:8 offset1:74
	s_waitcnt vmcnt(0)
	ds_write2_b32 v67, v126, v127 offset0:140 offset1:206
	v_add_u32_e32 v58, 0x840, v58
	s_cmp_lg_u32 s10, 0x80000
	s_waitcnt lgkmcnt(0)
	s_lshl_b32 s10, s2, 5
	ds_read2_b32 v[20:21], v38 offset1:33
	s_and_b32 s10, s10, 0x7e0
	s_waitcnt lgkmcnt(0)
	v_cvt_pk_bf16_f32 v20, v20, v21
	ds_read2_b32 v[22:23], v38 offset0:66 offset1:99
	s_add_i32 s8, s8, 0xffff6000
	v_or_b32_e32 v28, s10, v37
	s_waitcnt lgkmcnt(0)
	v_cvt_pk_bf16_f32 v21, v22, v23
	ds_read2_b32 v[22:23], v38 offset0:132 offset1:165
	v_lshl_add_u64 v[26:27], s[8:9], 1, v[0:1]
	v_lshlrev_b32_e32 v194, 14, v28
	s_waitcnt lgkmcnt(0)
	v_cvt_pk_bf16_f32 v22, v22, v23
	ds_read2_b32 v[24:25], v38 offset0:198 offset1:231
	s_waitcnt lgkmcnt(0)
	v_cvt_pk_bf16_f32 v23, v24, v25
	v_lshl_add_u64 v[28:29], v[26:27], 0, v[194:195]
	ds_read2_b32 v[24:25], v38 offset0:8 offset1:41
	global_store_dwordx4 v[28:29], v[20:23], off
	v_or_b32_e32 v28, s10, v39
	v_lshlrev_b32_e32 v194, 14, v28
	s_waitcnt lgkmcnt(0)
	v_cvt_pk_bf16_f32 v20, v24, v25
	ds_read2_b32 v[22:23], v38 offset0:74 offset1:107
	s_waitcnt lgkmcnt(0)
	v_cvt_pk_bf16_f32 v21, v22, v23
	ds_read2_b32 v[22:23], v38 offset0:140 offset1:173
	s_waitcnt lgkmcnt(0)
	v_cvt_pk_bf16_f32 v22, v22, v23
	ds_read2_b32 v[24:25], v38 offset0:206 offset1:239
	s_waitcnt lgkmcnt(0)
	v_cvt_pk_bf16_f32 v23, v24, v25
	v_lshl_add_u64 v[28:29], v[26:27], 0, v[194:195]
	ds_read2_b32 v[24:25], v38 offset0:16 offset1:49
	global_store_dwordx4 v[28:29], v[20:23], off
	v_or_b32_e32 v28, s10, v40
	v_lshlrev_b32_e32 v194, 14, v28
	s_waitcnt lgkmcnt(0)
	v_cvt_pk_bf16_f32 v20, v24, v25
	ds_read2_b32 v[22:23], v38 offset0:82 offset1:115
	s_waitcnt lgkmcnt(0)
	v_cvt_pk_bf16_f32 v21, v22, v23
	ds_read2_b32 v[22:23], v38 offset0:148 offset1:181
	s_waitcnt lgkmcnt(0)
	v_cvt_pk_bf16_f32 v22, v22, v23
	ds_read2_b32 v[24:25], v38 offset0:214 offset1:247
	s_waitcnt lgkmcnt(0)
	v_cvt_pk_bf16_f32 v23, v24, v25
	v_lshl_add_u64 v[28:29], v[26:27], 0, v[194:195]
	ds_read2_b32 v[24:25], v38 offset0:24 offset1:57
	global_store_dwordx4 v[28:29], v[20:23], off
	s_waitcnt lgkmcnt(0)
	s_nop 0
	v_cvt_pk_bf16_f32 v20, v24, v25
	ds_read2_b32 v[22:23], v38 offset0:90 offset1:123
	s_waitcnt lgkmcnt(0)
	v_cvt_pk_bf16_f32 v21, v22, v23
	ds_read2_b32 v[22:23], v38 offset0:156 offset1:189
	s_waitcnt lgkmcnt(0)
	v_cvt_pk_bf16_f32 v22, v22, v23
	v_or_b32_e32 v23, s10, v41
	ds_read2_b32 v[24:25], v38 offset0:222 offset1:255
	v_lshlrev_b32_e32 v194, 14, v23
	s_waitcnt lgkmcnt(0)
	v_cvt_pk_bf16_f32 v23, v24, v25
	v_lshl_add_u64 v[24:25], v[26:27], 0, v[194:195]
	global_store_dwordx4 v[24:25], v[20:23], off
	s_waitcnt lgkmcnt(0)
	s_mov_b64 s[10:11], 0

; __device__ __forceinline__ void p0_transpose_item(const float* W, int ld, int K, int nblk, bf16* WT, LAS float* scr, int item, int lane, bool cumap = false) {
;     ...
; #pragma unroll 8
;     for (int i = 0; i < 32; ++i) { const int kk = 2 * i + (lane >> 5); scr[kk * 33 + (lane & 31)] = __builtin_nontemporal_load(W + (size_t)(k0 + kk) * ld + n0 + (lane & 31)); }
.LBB0_600:
	v_lshl_add_u64 v[128:129], v[18:19], 0, s[10:11]
	v_lshl_add_u64 v[130:131], v[32:33], 0, s[10:11]
	v_lshl_add_u64 v[132:133], v[30:31], 0, s[10:11]
	v_lshl_add_u64 v[134:135], v[28:29], 0, s[10:11]
	v_lshl_add_u64 v[136:137], v[26:27], 0, s[10:11]
	v_lshl_add_u64 v[138:139], v[24:25], 0, s[10:11]
	v_lshl_add_u64 v[140:141], v[22:23], 0, s[10:11]
	v_lshl_add_u64 v[142:143], v[20:21], 0, s[10:11]
	global_load_dword v96, v[128:129], off nt
	global_load_dword v97, v[130:131], off nt
	global_load_dword v98, v[132:133], off nt
	global_load_dword v99, v[134:135], off nt
	global_load_dword v100, v[136:137], off nt
	global_load_dword v101, v[138:139], off nt
	global_load_dword v102, v[140:141], off nt
	global_load_dword v103, v[142:143], off nt
	s_add_u32 s10, s10, 0x20000
	s_addc_u32 s11, s11, 0
	v_lshl_add_u64 v[128:129], v[18:19], 0, s[10:11]
	v_lshl_add_u64 v[130:131], v[32:33], 0, s[10:11]
	v_lshl_add_u64 v[132:133], v[30:31], 0, s[10:11]
	v_lshl_add_u64 v[134:135], v[28:29], 0, s[10:11]
	v_lshl_add_u64 v[136:137], v[26:27], 0, s[10:11]
	v_lshl_add_u64 v[138:139], v[24:25], 0, s[10:11]
	v_lshl_add_u64 v[140:141], v[22:23], 0, s[10:11]
	v_lshl_add_u64 v[142:143], v[20:21], 0, s[10:11]
	global_load_dword v104, v[128:129], off nt
	global_load_dword v105, v[130:131], off nt
	global_load_dword v106, v[132:133], off nt
	global_load_dword v107, v[134:135], off nt
	global_load_dword v108, v[136:137], off nt
	global_load_dword v109, v[138:139], off nt
	global_load_dword v110, v[140:141], off nt
	global_load_dword v111, v[142:143], off nt
	s_add_u32 s10, s10, 0x20000
	s_addc_u32 s11, s11, 0
	v_lshl_add_u64 v[128:129], v[18:19], 0, s[10:11]
	v_lshl_add_u64 v[130:131], v[32:33], 0, s[10:11]
	v_lshl_add_u64 v[132:133], v[30:31], 0, s[10:11]
	v_lshl_add_u64 v[134:135], v[28:29], 0, s[10:11]
	v_lshl_add_u64 v[136:137], v[26:27], 0, s[10:11]
	v_lshl_add_u64 v[138:139], v[24:25], 0, s[10:11]
	v_lshl_add_u64 v[140:141], v[22:23], 0, s[10:11]
	v_lshl_add_u64 v[142:143], v[20:21], 0, s[10:11]
	global_load_dword v112, v[128:129], off nt
	global_load_dword v113, v[130:131], off nt
	global_load_dword v114, v[132:133], off nt
	global_load_dword v115, v[134:135], off nt
	global_load_dword v116, v[136:137], off nt
	global_load_dword v117, v[138:139], off nt
	global_load_dword v118, v[140:141], off nt
	global_load_dword v119, v[142:143], off nt
	s_add_u32 s10, s10, 0x20000
	s_addc_u32 s11, s11, 0
	v_lshl_add_u64 v[128:129], v[18:19], 0, s[10:11]
	v_lshl_add_u64 v[130:131], v[32:33], 0, s[10:11]
	v_lshl_add_u64 v[132:133], v[30:31], 0, s[10:11]
	v_lshl_add_u64 v[134:135], v[28:29], 0, s[10:11]
	v_lshl_add_u64 v[136:137], v[26:27], 0, s[10:11]
	v_lshl_add_u64 v[138:139], v[24:25], 0, s[10:11]
	v_lshl_add_u64 v[140:141], v[22:23], 0, s[10:11]
	v_lshl_add_u64 v[142:143], v[20:21], 0, s[10:11]
	global_load_dword v120, v[128:129], off nt
	global_load_dword v121, v[130:131], off nt
	global_load_dword v122, v[132:133], off nt
	global_load_dword v123, v[134:135], off nt
	global_load_dword v124, v[136:137], off nt
	global_load_dword v125, v[138:139], off nt
	global_load_dword v126, v[140:141], off nt
	global_load_dword v127, v[142:143], off nt
	s_add_u32 s10, s10, 0x20000
	s_addc_u32 s11, s11, 0
	v_add_u32_e32 v65, 0x400, v34
	s_waitcnt vmcnt(30)
	ds_write2_b32 v34, v96, v97 offset1:66
	s_waitcnt vmcnt(28)
	ds_write2_b32 v34, v98, v99 offset0:132 offset1:198
	s_waitcnt vmcnt(26)
	ds_write2_b32 v65, v100, v101 offset0:8 offset1:74
	s_waitcnt vmcnt(24)
	ds_write2_b32 v65, v102, v103 offset0:140 offset1:206
	v_add_u32_e32 v34, 0x840, v34
	v_add_u32_e32 v65, 0x400, v34
	s_waitcnt vmcnt(22)
; #define LAS __attribute__((address_space(3)))
; #define LDS_WAIT() asm volatile("s_waitcnt lgkmcnt(0)" ::: "memory")
; __device__ __forceinline__ unsigned pk2(float lo, float hi) { unsigned r; asm volatile("v_cvt_pk_bf16_f32 %0, %1, %2" : "=v"(r) : "v"(lo), "v"(hi)); return r; }
; __device__ __forceinline__ void p0_transpose_item(const float* W, int ld, int K, int nblk, bf16* WT, LAS float* scr, int item, int lane, bool cumap = false) {
;     ...
;     for (int i = 0; i < 32; ++i) { const int kk = 2 * i + (lane >> 5); scr[kk * 33 + (lane & 31)] = __builtin_nontemporal_load(W + (size_t)(k0 + kk) * ld + n0 + (lane & 31)); }
;     LDS_WAIT(); asm volatile("" ::: "memory");
;     const int c = lane & 7;
; #pragma unroll
;     for (int j = 0; j < 4; ++j) { const int n = (lane >> 3) + 8 * j; const LAS float* s = scr + (8 * c) * 33 + n;
;         v4u o; o.x = pk2(s[0 * 33], s[1 * 33]); o.y = pk2(s[2 * 33], s[3 * 33]); o.z = pk2(s[4 * 33], s[5 * 33]); o.w = pk2(s[6 * 33], s[7 * 33]);
;         *(v4u*)(WT + (size_t)(d0 + n) * K + k0 + 8 * c) = o; }
;     LDS_WAIT(); asm volatile("" ::: "memory");
	ds_write2_b32 v34, v104, v105 offset1:66
	s_waitcnt vmcnt(20)
	ds_write2_b32 v34, v106, v107 offset0:132 offset1:198
	s_waitcnt vmcnt(18)
	ds_write2_b32 v65, v108, v109 offset0:8 offset1:74
	s_waitcnt vmcnt(16)
	ds_write2_b32 v65, v110, v111 offset0:140 offset1:206
	v_add_u32_e32 v34, 0x840, v34
	v_add_u32_e32 v65, 0x400, v34
	s_waitcnt vmcnt(14)
	ds_write2_b32 v34, v112, v113 offset1:66
	s_waitcnt vmcnt(12)
	ds_write2_b32 v34, v114, v115 offset0:132 offset1:198
	s_waitcnt vmcnt(10)
	ds_write2_b32 v65, v116, v117 offset0:8 offset1:74
	s_waitcnt vmcnt(8)
	ds_write2_b32 v65, v118, v119 offset0:140 offset1:206
	v_add_u32_e32 v34, 0x840, v34
	v_add_u32_e32 v65, 0x400, v34
	s_waitcnt vmcnt(6)
	ds_write2_b32 v34, v120, v121 offset1:66
	s_waitcnt vmcnt(4)
	ds_write2_b32 v34, v122, v123 offset0:132 offset1:198
	s_waitcnt vmcnt(2)
	ds_write2_b32 v65, v124, v125 offset0:8 offset1:74
	s_waitcnt vmcnt(0)
	ds_write2_b32 v65, v126, v127 offset0:140 offset1:206
	v_add_u32_e32 v34, 0x840, v34
	s_cmp_lg_u32 s10, 0x80000
	s_waitcnt lgkmcnt(0)
	s_lshl_b32 s10, s2, 5
	ds_read2_b32 v[18:19], v38 offset1:33
	s_and_b32 s10, s10, 0x7e0
	s_waitcnt lgkmcnt(0)
	v_cvt_pk_bf16_f32 v18, v18, v19
	ds_read2_b32 v[20:21], v38 offset0:66 offset1:99
	s_lshl_b32 s8, s8, 1
	v_or_b32_e32 v26, s10, v37
	s_waitcnt lgkmcnt(0)
	v_cvt_pk_bf16_f32 v19, v20, v21
	ds_read2_b32 v[20:21], v38 offset0:132 offset1:165
	v_lshl_add_u64 v[24:25], v[2:3], 0, s[8:9]
	v_lshlrev_b32_e32 v194, 14, v26
	s_waitcnt lgkmcnt(0)
	v_cvt_pk_bf16_f32 v20, v20, v21
	ds_read2_b32 v[22:23], v38 offset0:198 offset1:231
	s_waitcnt lgkmcnt(0)
	v_cvt_pk_bf16_f32 v21, v22, v23
	v_lshl_add_u64 v[26:27], v[24:25], 0, v[194:195]
	ds_read2_b32 v[22:23], v38 offset0:8 offset1:41
	global_store_dwordx4 v[26:27], v[18:21], off
	v_or_b32_e32 v26, s10, v39
	v_lshlrev_b32_e32 v194, 14, v26
	s_waitcnt lgkmcnt(0)
	v_cvt_pk_bf16_f32 v18, v22, v23
	ds_read2_b32 v[20:21], v38 offset0:74 offset1:107
	s_waitcnt lgkmcnt(0)
	v_cvt_pk_bf16_f32 v19, v20, v21
	ds_read2_b32 v[20:21], v38 offset0:140 offset1:173
	s_waitcnt lgkmcnt(0)
	v_cvt_pk_bf16_f32 v20, v20, v21
	ds_read2_b32 v[22:23], v38 offset0:206 offset1:239
	s_waitcnt lgkmcnt(0)
	v_cvt_pk_bf16_f32 v21, v22, v23
	v_lshl_add_u64 v[26:27], v[24:25], 0, v[194:195]
	ds_read2_b32 v[22:23], v38 offset0:16 offset1:49
	global_store_dwordx4 v[26:27], v[18:21], off
	v_or_b32_e32 v26, s10, v40
	v_lshlrev_b32_e32 v194, 14, v26
	s_waitcnt lgkmcnt(0)
	v_cvt_pk_bf16_f32 v18, v22, v23
	ds_read2_b32 v[20:21], v38 offset0:82 offset1:115
	s_waitcnt lgkmcnt(0)
	v_cvt_pk_bf16_f32 v19, v20, v21
	ds_read2_b32 v[20:21], v38 offset0:148 offset1:181
	s_waitcnt lgkmcnt(0)
	v_cvt_pk_bf16_f32 v20, v20, v21
	ds_read2_b32 v[22:23], v38 offset0:214 offset1:247
	s_waitcnt lgkmcnt(0)
	v_cvt_pk_bf16_f32 v21, v22, v23
	v_lshl_add_u64 v[26:27], v[24:25], 0, v[194:195]
	ds_read2_b32 v[22:23], v38 offset0:24 offset1:57
	global_store_dwordx4 v[26:27], v[18:21], off
	s_waitcnt lgkmcnt(0)
	s_nop 0
	v_cvt_pk_bf16_f32 v18, v22, v23
	ds_read2_b32 v[20:21], v38 offset0:90 offset1:123
	s_waitcnt lgkmcnt(0)
	v_cvt_pk_bf16_f32 v19, v20, v21
	ds_read2_b32 v[20:21], v38 offset0:156 offset1:189
	s_waitcnt lgkmcnt(0)
	v_cvt_pk_bf16_f32 v20, v20, v21
	v_or_b32_e32 v21, s10, v41
	ds_read2_b32 v[22:23], v38 offset0:222 offset1:255
	v_lshlrev_b32_e32 v194, 14, v21
	s_waitcnt lgkmcnt(0)
	v_cvt_pk_bf16_f32 v21, v22, v23
	v_lshl_add_u64 v[22:23], v[24:25], 0, v[194:195]
	global_store_dwordx4 v[22:23], v[18:21], off
	s_waitcnt lgkmcnt(0)

; __device__ __forceinline__ void p0_transpose_item(const float* W, int ld, int K, int nblk, bf16* WT, LAS float* scr, int item, int lane, bool cumap = false) {
;     ...
; #pragma unroll 8
;     for (int i = 0; i < 32; ++i) { const int kk = 2 * i + (lane >> 5); scr[kk * 33 + (lane & 31)] = __builtin_nontemporal_load(W + (size_t)(k0 + kk) * ld + n0 + (lane & 31)); }
.LBB0_605:
	v_lshl_add_u64 v[128:129], v[32:33], 0, s[10:11]
	v_lshl_add_u64 v[130:131], v[30:31], 0, s[10:11]
	v_lshl_add_u64 v[132:133], v[28:29], 0, s[10:11]
	v_lshl_add_u64 v[134:135], v[26:27], 0, s[10:11]
	v_lshl_add_u64 v[136:137], v[24:25], 0, s[10:11]
	v_lshl_add_u64 v[138:139], v[22:23], 0, s[10:11]
	v_lshl_add_u64 v[140:141], v[20:21], 0, s[10:11]
	v_lshl_add_u64 v[142:143], v[18:19], 0, s[10:11]
	global_load_dword v96, v[128:129], off nt
	global_load_dword v97, v[130:131], off nt
	global_load_dword v98, v[132:133], off nt
	global_load_dword v99, v[134:135], off nt
	global_load_dword v100, v[136:137], off nt
	global_load_dword v101, v[138:139], off nt
	global_load_dword v102, v[140:141], off nt
	global_load_dword v103, v[142:143], off nt
	s_add_u32 s10, s10, 0x80000
	s_addc_u32 s11, s11, 0
	v_lshl_add_u64 v[128:129], v[32:33], 0, s[10:11]
	v_lshl_add_u64 v[130:131], v[30:31], 0, s[10:11]
	v_lshl_add_u64 v[132:133], v[28:29], 0, s[10:11]
	v_lshl_add_u64 v[134:135], v[26:27], 0, s[10:11]
	v_lshl_add_u64 v[136:137], v[24:25], 0, s[10:11]
	v_lshl_add_u64 v[138:139], v[22:23], 0, s[10:11]
	v_lshl_add_u64 v[140:141], v[20:21], 0, s[10:11]
	v_lshl_add_u64 v[142:143], v[18:19], 0, s[10:11]
	global_load_dword v104, v[128:129], off nt
	global_load_dword v105, v[130:131], off nt
	global_load_dword v106, v[132:133], off nt
	global_load_dword v107, v[134:135], off nt
	global_load_dword v108, v[136:137], off nt
	global_load_dword v109, v[138:139], off nt
	global_load_dword v110, v[140:141], off nt
	global_load_dword v111, v[142:143], off nt
	s_add_u32 s10, s10, 0x80000
	s_addc_u32 s11, s11, 0
	v_lshl_add_u64 v[128:129], v[32:33], 0, s[10:11]
	v_lshl_add_u64 v[130:131], v[30:31], 0, s[10:11]
	v_lshl_add_u64 v[132:133], v[28:29], 0, s[10:11]
	v_lshl_add_u64 v[134:135], v[26:27], 0, s[10:11]
	v_lshl_add_u64 v[136:137], v[24:25], 0, s[10:11]
	v_lshl_add_u64 v[138:139], v[22:23], 0, s[10:11]
	v_lshl_add_u64 v[140:141], v[20:21], 0, s[10:11]
	v_lshl_add_u64 v[142:143], v[18:19], 0, s[10:11]
	global_load_dword v112, v[128:129], off nt
	global_load_dword v113, v[130:131], off nt
	global_load_dword v114, v[132:133], off nt
	global_load_dword v115, v[134:135], off nt
	global_load_dword v116, v[136:137], off nt
	global_load_dword v117, v[138:139], off nt
	global_load_dword v118, v[140:141], off nt
	global_load_dword v119, v[142:143], off nt
	s_add_u32 s10, s10, 0x80000
	s_addc_u32 s11, s11, 0
	v_lshl_add_u64 v[128:129], v[32:33], 0, s[10:11]
	v_lshl_add_u64 v[130:131], v[30:31], 0, s[10:11]
	v_lshl_add_u64 v[132:133], v[28:29], 0, s[10:11]
	v_lshl_add_u64 v[134:135], v[26:27], 0, s[10:11]
	v_lshl_add_u64 v[136:137], v[24:25], 0, s[10:11]
	v_lshl_add_u64 v[138:139], v[22:23], 0, s[10:11]
	v_lshl_add_u64 v[140:141], v[20:21], 0, s[10:11]
	v_lshl_add_u64 v[142:143], v[18:19], 0, s[10:11]
	global_load_dword v120, v[128:129], off nt
	global_load_dword v121, v[130:131], off nt
	global_load_dword v122, v[132:133], off nt
	global_load_dword v123, v[134:135], off nt
	global_load_dword v124, v[136:137], off nt
	global_load_dword v125, v[138:139], off nt
	global_load_dword v126, v[140:141], off nt
	global_load_dword v127, v[142:143], off nt
	s_add_u32 s10, s10, 0x80000
	s_addc_u32 s11, s11, 0
	v_add_u32_e32 v65, 0x400, v34
	s_waitcnt vmcnt(30)
	ds_write2_b32 v34, v96, v97 offset1:66
	s_waitcnt vmcnt(28)
	ds_write2_b32 v34, v98, v99 offset0:132 offset1:198
	s_waitcnt vmcnt(26)
	ds_write2_b32 v65, v100, v101 offset0:8 offset1:74
	s_waitcnt vmcnt(24)
	ds_write2_b32 v65, v102, v103 offset0:140 offset1:206
	v_add_u32_e32 v34, 0x840, v34
	v_add_u32_e32 v65, 0x400, v34
	s_waitcnt vmcnt(22)
; #define LAS __attribute__((address_space(3)))
; #define LDS_WAIT() asm volatile("s_waitcnt lgkmcnt(0)" ::: "memory")
; __device__ __forceinline__ unsigned pk2(float lo, float hi) { unsigned r; asm volatile("v_cvt_pk_bf16_f32 %0, %1, %2" : "=v"(r) : "v"(lo), "v"(hi)); return r; }
; __device__ __forceinline__ void p0_transpose_item(const float* W, int ld, int K, int nblk, bf16* WT, LAS float* scr, int item, int lane, bool cumap = false) {
;     ...
;     for (int i = 0; i < 32; ++i) { const int kk = 2 * i + (lane >> 5); scr[kk * 33 + (lane & 31)] = __builtin_nontemporal_load(W + (size_t)(k0 + kk) * ld + n0 + (lane & 31)); }
;     LDS_WAIT(); asm volatile("" ::: "memory");
;     const int c = lane & 7;
; #pragma unroll
;     for (int j = 0; j < 4; ++j) { const int n = (lane >> 3) + 8 * j; const LAS float* s = scr + (8 * c) * 33 + n;
;         v4u o; o.x = pk2(s[0 * 33], s[1 * 33]); o.y = pk2(s[2 * 33], s[3 * 33]); o.z = pk2(s[4 * 33], s[5 * 33]); o.w = pk2(s[6 * 33], s[7 * 33]);
;         *(v4u*)(WT + (size_t)(d0 + n) * K + k0 + 8 * c) = o; }
;     LDS_WAIT(); asm volatile("" ::: "memory");
	ds_write2_b32 v34, v104, v105 offset1:66
	s_waitcnt vmcnt(20)
	ds_write2_b32 v34, v106, v107 offset0:132 offset1:198
	s_waitcnt vmcnt(18)
	ds_write2_b32 v65, v108, v109 offset0:8 offset1:74
	s_waitcnt vmcnt(16)
	ds_write2_b32 v65, v110, v111 offset0:140 offset1:206
	v_add_u32_e32 v34, 0x840, v34
	v_add_u32_e32 v65, 0x400, v34
	s_waitcnt vmcnt(14)
	ds_write2_b32 v34, v112, v113 offset1:66
	s_waitcnt vmcnt(12)
	ds_write2_b32 v34, v114, v115 offset0:132 offset1:198
	s_waitcnt vmcnt(10)
	ds_write2_b32 v65, v116, v117 offset0:8 offset1:74
	s_waitcnt vmcnt(8)
	ds_write2_b32 v65, v118, v119 offset0:140 offset1:206
	v_add_u32_e32 v34, 0x840, v34
	v_add_u32_e32 v65, 0x400, v34
	s_waitcnt vmcnt(6)
	ds_write2_b32 v34, v120, v121 offset1:66
	s_waitcnt vmcnt(4)
	ds_write2_b32 v34, v122, v123 offset0:132 offset1:198
	s_waitcnt vmcnt(2)
	ds_write2_b32 v65, v124, v125 offset0:8 offset1:74
	s_waitcnt vmcnt(0)
	ds_write2_b32 v65, v126, v127 offset0:140 offset1:206
	v_add_u32_e32 v34, 0x840, v34
	s_cmp_lg_u32 s10, 0x200000
	s_waitcnt lgkmcnt(0)
	s_add_i32 s8, s2, 0xa000
	s_lshl_b32 s10, s2, 5
	ds_read2_b32 v[18:19], v38 offset1:33
	s_and_b32 s10, s10, 0x1fe0
	s_bfe_u32 s8, s8, 0x80008
	s_waitcnt lgkmcnt(0)
	v_cvt_pk_bf16_f32 v18, v18, v19
	ds_read2_b32 v[20:21], v38 offset0:66 offset1:99
	s_lshl_b32 s8, s8, 7
	v_or_b32_e32 v26, s10, v37
	s_waitcnt lgkmcnt(0)
	v_cvt_pk_bf16_f32 v19, v20, v21
	ds_read2_b32 v[20:21], v38 offset0:132 offset1:165
	v_lshl_add_u64 v[24:25], v[4:5], 0, s[8:9]
	v_lshlrev_b32_e32 v194, 12, v26
	s_waitcnt lgkmcnt(0)
	v_cvt_pk_bf16_f32 v20, v20, v21
	ds_read2_b32 v[22:23], v38 offset0:198 offset1:231
	s_waitcnt lgkmcnt(0)
	v_cvt_pk_bf16_f32 v21, v22, v23
	v_lshl_add_u64 v[26:27], v[24:25], 0, v[194:195]
	ds_read2_b32 v[22:23], v38 offset0:8 offset1:41
	global_store_dwordx4 v[26:27], v[18:21], off
	v_or_b32_e32 v26, s10, v39
	v_lshlrev_b32_e32 v194, 12, v26
	s_waitcnt lgkmcnt(0)
	v_cvt_pk_bf16_f32 v18, v22, v23
	ds_read2_b32 v[20:21], v38 offset0:74 offset1:107
	s_waitcnt lgkmcnt(0)
	v_cvt_pk_bf16_f32 v19, v20, v21
	ds_read2_b32 v[20:21], v38 offset0:140 offset1:173
	s_waitcnt lgkmcnt(0)
	v_cvt_pk_bf16_f32 v20, v20, v21
	ds_read2_b32 v[22:23], v38 offset0:206 offset1:239
	s_waitcnt lgkmcnt(0)
	v_cvt_pk_bf16_f32 v21, v22, v23
	v_lshl_add_u64 v[26:27], v[24:25], 0, v[194:195]
	ds_read2_b32 v[22:23], v38 offset0:16 offset1:49
	global_store_dwordx4 v[26:27], v[18:21], off
	v_or_b32_e32 v26, s10, v40
	v_lshlrev_b32_e32 v194, 12, v26
	s_waitcnt lgkmcnt(0)
	v_cvt_pk_bf16_f32 v18, v22, v23
	ds_read2_b32 v[20:21], v38 offset0:82 offset1:115
	s_waitcnt lgkmcnt(0)
	v_cvt_pk_bf16_f32 v19, v20, v21
	ds_read2_b32 v[20:21], v38 offset0:148 offset1:181
	s_waitcnt lgkmcnt(0)
	v_cvt_pk_bf16_f32 v20, v20, v21
	ds_read2_b32 v[22:23], v38 offset0:214 offset1:247
	s_waitcnt lgkmcnt(0)
	v_cvt_pk_bf16_f32 v21, v22, v23
	v_lshl_add_u64 v[26:27], v[24:25], 0, v[194:195]
	ds_read2_b32 v[22:23], v38 offset0:24 offset1:57
	global_store_dwordx4 v[26:27], v[18:21], off
	s_waitcnt lgkmcnt(0)
	s_nop 0
	v_cvt_pk_bf16_f32 v18, v22, v23
	ds_read2_b32 v[20:21], v38 offset0:90 offset1:123
	s_waitcnt lgkmcnt(0)
	v_cvt_pk_bf16_f32 v19, v20, v21
	ds_read2_b32 v[20:21], v38 offset0:156 offset1:189
	s_waitcnt lgkmcnt(0)
	v_cvt_pk_bf16_f32 v20, v20, v21
	v_or_b32_e32 v21, s10, v41
	ds_read2_b32 v[22:23], v38 offset0:222 offset1:255
	v_lshlrev_b32_e32 v194, 12, v21
	s_waitcnt lgkmcnt(0)
	v_cvt_pk_bf16_f32 v21, v22, v23
	v_lshl_add_u64 v[22:23], v[24:25], 0, v[194:195]
	global_store_dwordx4 v[22:23], v[18:21], off
	s_waitcnt lgkmcnt(0)

; __device__ __forceinline__ void p0_transpose_item(const float* W, int ld, int K, int nblk, bf16* WT, LAS float* scr, int item, int lane, bool cumap = false) {
;     ...
; #pragma unroll 8
;     for (int i = 0; i < 32; ++i) { const int kk = 2 * i + (lane >> 5); scr[kk * 33 + (lane & 31)] = __builtin_nontemporal_load(W + (size_t)(k0 + kk) * ld + n0 + (lane & 31)); }
.LBB0_610:
	v_lshl_add_u64 v[128:129], v[32:33], 0, s[10:11]
	v_lshl_add_u64 v[130:131], v[30:31], 0, s[10:11]
	v_lshl_add_u64 v[132:133], v[28:29], 0, s[10:11]
	v_lshl_add_u64 v[134:135], v[26:27], 0, s[10:11]
	v_lshl_add_u64 v[136:137], v[24:25], 0, s[10:11]
	v_lshl_add_u64 v[138:139], v[22:23], 0, s[10:11]
	v_lshl_add_u64 v[140:141], v[20:21], 0, s[10:11]
	v_lshl_add_u64 v[142:143], v[18:19], 0, s[10:11]
	global_load_dword v96, v[128:129], off nt
	global_load_dword v97, v[130:131], off nt
	global_load_dword v98, v[132:133], off nt
	global_load_dword v99, v[134:135], off nt
	global_load_dword v100, v[136:137], off nt
	global_load_dword v101, v[138:139], off nt
	global_load_dword v102, v[140:141], off nt
	global_load_dword v103, v[142:143], off nt
	s_add_u32 s10, s10, 0x80000
	s_addc_u32 s11, s11, 0
	v_lshl_add_u64 v[128:129], v[32:33], 0, s[10:11]
	v_lshl_add_u64 v[130:131], v[30:31], 0, s[10:11]
	v_lshl_add_u64 v[132:133], v[28:29], 0, s[10:11]
	v_lshl_add_u64 v[134:135], v[26:27], 0, s[10:11]
	v_lshl_add_u64 v[136:137], v[24:25], 0, s[10:11]
	v_lshl_add_u64 v[138:139], v[22:23], 0, s[10:11]
	v_lshl_add_u64 v[140:141], v[20:21], 0, s[10:11]
	v_lshl_add_u64 v[142:143], v[18:19], 0, s[10:11]
	global_load_dword v104, v[128:129], off nt
	global_load_dword v105, v[130:131], off nt
	global_load_dword v106, v[132:133], off nt
	global_load_dword v107, v[134:135], off nt
	global_load_dword v108, v[136:137], off nt
	global_load_dword v109, v[138:139], off nt
	global_load_dword v110, v[140:141], off nt
	global_load_dword v111, v[142:143], off nt
	s_add_u32 s10, s10, 0x80000
	s_addc_u32 s11, s11, 0
	v_lshl_add_u64 v[128:129], v[32:33], 0, s[10:11]
	v_lshl_add_u64 v[130:131], v[30:31], 0, s[10:11]
	v_lshl_add_u64 v[132:133], v[28:29], 0, s[10:11]
	v_lshl_add_u64 v[134:135], v[26:27], 0, s[10:11]
	v_lshl_add_u64 v[136:137], v[24:25], 0, s[10:11]
	v_lshl_add_u64 v[138:139], v[22:23], 0, s[10:11]
	v_lshl_add_u64 v[140:141], v[20:21], 0, s[10:11]
	v_lshl_add_u64 v[142:143], v[18:19], 0, s[10:11]
	global_load_dword v112, v[128:129], off nt
	global_load_dword v113, v[130:131], off nt
	global_load_dword v114, v[132:133], off nt
	global_load_dword v115, v[134:135], off nt
	global_load_dword v116, v[136:137], off nt
	global_load_dword v117, v[138:139], off nt
	global_load_dword v118, v[140:141], off nt
	global_load_dword v119, v[142:143], off nt
	s_add_u32 s10, s10, 0x80000
	s_addc_u32 s11, s11, 0
	v_lshl_add_u64 v[128:129], v[32:33], 0, s[10:11]
	v_lshl_add_u64 v[130:131], v[30:31], 0, s[10:11]
	v_lshl_add_u64 v[132:133], v[28:29], 0, s[10:11]
	v_lshl_add_u64 v[134:135], v[26:27], 0, s[10:11]
	v_lshl_add_u64 v[136:137], v[24:25], 0, s[10:11]
	v_lshl_add_u64 v[138:139], v[22:23], 0, s[10:11]
	v_lshl_add_u64 v[140:141], v[20:21], 0, s[10:11]
	v_lshl_add_u64 v[142:143], v[18:19], 0, s[10:11]
	global_load_dword v120, v[128:129], off nt
	global_load_dword v121, v[130:131], off nt
	global_load_dword v122, v[132:133], off nt
	global_load_dword v123, v[134:135], off nt
	global_load_dword v124, v[136:137], off nt
	global_load_dword v125, v[138:139], off nt
	global_load_dword v126, v[140:141], off nt
	global_load_dword v127, v[142:143], off nt
	s_add_u32 s10, s10, 0x80000
	s_addc_u32 s11, s11, 0
	v_add_u32_e32 v65, 0x400, v34
	s_waitcnt vmcnt(30)
	ds_write2_b32 v34, v96, v97 offset1:66
	s_waitcnt vmcnt(28)
	ds_write2_b32 v34, v98, v99 offset0:132 offset1:198
	s_waitcnt vmcnt(26)
	ds_write2_b32 v65, v100, v101 offset0:8 offset1:74
	s_waitcnt vmcnt(24)
	ds_write2_b32 v65, v102, v103 offset0:140 offset1:206
	v_add_u32_e32 v34, 0x840, v34
	v_add_u32_e32 v65, 0x400, v34
	s_waitcnt vmcnt(22)
; #define LAS __attribute__((address_space(3)))
; #define LDS_WAIT() asm volatile("s_waitcnt lgkmcnt(0)" ::: "memory")
; __device__ __forceinline__ unsigned pk2(float lo, float hi) { unsigned r; asm volatile("v_cvt_pk_bf16_f32 %0, %1, %2" : "=v"(r) : "v"(lo), "v"(hi)); return r; }
; __device__ __forceinline__ void p0_transpose_item(const float* W, int ld, int K, int nblk, bf16* WT, LAS float* scr, int item, int lane, bool cumap = false) {
;     ...
;     for (int i = 0; i < 32; ++i) { const int kk = 2 * i + (lane >> 5); scr[kk * 33 + (lane & 31)] = __builtin_nontemporal_load(W + (size_t)(k0 + kk) * ld + n0 + (lane & 31)); }
;     LDS_WAIT(); asm volatile("" ::: "memory");
;     const int c = lane & 7;
; #pragma unroll
;     for (int j = 0; j < 4; ++j) { const int n = (lane >> 3) + 8 * j; const LAS float* s = scr + (8 * c) * 33 + n;
;         v4u o; o.x = pk2(s[0 * 33], s[1 * 33]); o.y = pk2(s[2 * 33], s[3 * 33]); o.z = pk2(s[4 * 33], s[5 * 33]); o.w = pk2(s[6 * 33], s[7 * 33]);
;         *(v4u*)(WT + (size_t)(d0 + n) * K + k0 + 8 * c) = o; }
;     LDS_WAIT(); asm volatile("" ::: "memory");
	ds_write2_b32 v34, v104, v105 offset1:66
	s_waitcnt vmcnt(20)
	ds_write2_b32 v34, v106, v107 offset0:132 offset1:198
	s_waitcnt vmcnt(18)
	ds_write2_b32 v65, v108, v109 offset0:8 offset1:74
	s_waitcnt vmcnt(16)
	ds_write2_b32 v65, v110, v111 offset0:140 offset1:206
	v_add_u32_e32 v34, 0x840, v34
	v_add_u32_e32 v65, 0x400, v34
	s_waitcnt vmcnt(14)
	ds_write2_b32 v34, v112, v113 offset1:66
	s_waitcnt vmcnt(12)
	ds_write2_b32 v34, v114, v115 offset0:132 offset1:198
	s_waitcnt vmcnt(10)
	ds_write2_b32 v65, v116, v117 offset0:8 offset1:74
	s_waitcnt vmcnt(8)
	ds_write2_b32 v65, v118, v119 offset0:140 offset1:206
	v_add_u32_e32 v34, 0x840, v34
	v_add_u32_e32 v65, 0x400, v34
	s_waitcnt vmcnt(6)
	ds_write2_b32 v34, v120, v121 offset1:66
	s_waitcnt vmcnt(4)
	ds_write2_b32 v34, v122, v123 offset0:132 offset1:198
	s_waitcnt vmcnt(2)
	ds_write2_b32 v65, v124, v125 offset0:8 offset1:74
	s_waitcnt vmcnt(0)
	ds_write2_b32 v65, v126, v127 offset0:140 offset1:206
	v_add_u32_e32 v34, 0x840, v34
	s_cmp_lg_u32 s10, 0x200000
	s_waitcnt lgkmcnt(0)
	s_add_i32 s8, s2, 0xc000
	s_lshl_b32 s10, s2, 5
	ds_read2_b32 v[18:19], v38 offset1:33
	s_and_b32 s10, s10, 0x1fe0
	s_bfe_u32 s8, s8, 0x80008
	s_waitcnt lgkmcnt(0)
	v_cvt_pk_bf16_f32 v18, v18, v19
	ds_read2_b32 v[20:21], v38 offset0:66 offset1:99
	s_lshl_b32 s8, s8, 7
	v_or_b32_e32 v26, s10, v37
	s_waitcnt lgkmcnt(0)
	v_cvt_pk_bf16_f32 v19, v20, v21
	ds_read2_b32 v[20:21], v38 offset0:132 offset1:165
	v_lshl_add_u64 v[24:25], v[6:7], 0, s[8:9]
	v_lshlrev_b32_e32 v194, 12, v26
	s_waitcnt lgkmcnt(0)
	v_cvt_pk_bf16_f32 v20, v20, v21
	ds_read2_b32 v[22:23], v38 offset0:198 offset1:231
	s_waitcnt lgkmcnt(0)
	v_cvt_pk_bf16_f32 v21, v22, v23
	v_lshl_add_u64 v[26:27], v[24:25], 0, v[194:195]
	ds_read2_b32 v[22:23], v38 offset0:8 offset1:41
	global_store_dwordx4 v[26:27], v[18:21], off
	v_or_b32_e32 v26, s10, v39
	v_lshlrev_b32_e32 v194, 12, v26
	s_waitcnt lgkmcnt(0)
	v_cvt_pk_bf16_f32 v18, v22, v23
	ds_read2_b32 v[20:21], v38 offset0:74 offset1:107
	s_waitcnt lgkmcnt(0)
	v_cvt_pk_bf16_f32 v19, v20, v21
	ds_read2_b32 v[20:21], v38 offset0:140 offset1:173
	s_waitcnt lgkmcnt(0)
	v_cvt_pk_bf16_f32 v20, v20, v21
	ds_read2_b32 v[22:23], v38 offset0:206 offset1:239
	s_waitcnt lgkmcnt(0)
	v_cvt_pk_bf16_f32 v21, v22, v23
	v_lshl_add_u64 v[26:27], v[24:25], 0, v[194:195]
	ds_read2_b32 v[22:23], v38 offset0:16 offset1:49
	global_store_dwordx4 v[26:27], v[18:21], off
	v_or_b32_e32 v26, s10, v40
	v_lshlrev_b32_e32 v194, 12, v26
	s_waitcnt lgkmcnt(0)
	v_cvt_pk_bf16_f32 v18, v22, v23
	ds_read2_b32 v[20:21], v38 offset0:82 offset1:115
	s_waitcnt lgkmcnt(0)
	v_cvt_pk_bf16_f32 v19, v20, v21
	ds_read2_b32 v[20:21], v38 offset0:148 offset1:181
	s_waitcnt lgkmcnt(0)
	v_cvt_pk_bf16_f32 v20, v20, v21
	ds_read2_b32 v[22:23], v38 offset0:214 offset1:247
	s_waitcnt lgkmcnt(0)
	v_cvt_pk_bf16_f32 v21, v22, v23
	v_lshl_add_u64 v[26:27], v[24:25], 0, v[194:195]
	ds_read2_b32 v[22:23], v38 offset0:24 offset1:57
	global_store_dwordx4 v[26:27], v[18:21], off
	s_waitcnt lgkmcnt(0)
	s_nop 0
	v_cvt_pk_bf16_f32 v18, v22, v23
	ds_read2_b32 v[20:21], v38 offset0:90 offset1:123
	s_waitcnt lgkmcnt(0)
	v_cvt_pk_bf16_f32 v19, v20, v21
	ds_read2_b32 v[20:21], v38 offset0:156 offset1:189
	s_waitcnt lgkmcnt(0)
	v_cvt_pk_bf16_f32 v20, v20, v21
	v_or_b32_e32 v21, s10, v41
	ds_read2_b32 v[22:23], v38 offset0:222 offset1:255
	v_lshlrev_b32_e32 v194, 12, v21
	s_waitcnt lgkmcnt(0)
	v_cvt_pk_bf16_f32 v21, v22, v23
	v_lshl_add_u64 v[22:23], v[24:25], 0, v[194:195]
	global_store_dwordx4 v[22:23], v[18:21], off
	s_waitcnt lgkmcnt(0)

; __device__ __forceinline__ void p0_transpose_item(const float* W, int ld, int K, int nblk, bf16* WT, LAS float* scr, int item, int lane, bool cumap = false) {
;     ...
; #pragma unroll 8
;     for (int i = 0; i < 32; ++i) { const int kk = 2 * i + (lane >> 5); scr[kk * 33 + (lane & 31)] = __builtin_nontemporal_load(W + (size_t)(k0 + kk) * ld + n0 + (lane & 31)); }
.LBB0_615:
	v_lshl_add_u64 v[128:129], v[32:33], 0, s[10:11]
	v_lshl_add_u64 v[130:131], v[30:31], 0, s[10:11]
	v_lshl_add_u64 v[132:133], v[28:29], 0, s[10:11]
	v_lshl_add_u64 v[134:135], v[26:27], 0, s[10:11]
	v_lshl_add_u64 v[136:137], v[24:25], 0, s[10:11]
	v_lshl_add_u64 v[138:139], v[22:23], 0, s[10:11]
	v_lshl_add_u64 v[140:141], v[20:21], 0, s[10:11]
	v_lshl_add_u64 v[142:143], v[18:19], 0, s[10:11]
	global_load_dword v96, v[128:129], off nt
	global_load_dword v97, v[130:131], off nt
	global_load_dword v98, v[132:133], off nt
	global_load_dword v99, v[134:135], off nt
	global_load_dword v100, v[136:137], off nt
	global_load_dword v101, v[138:139], off nt
	global_load_dword v102, v[140:141], off nt
	global_load_dword v103, v[142:143], off nt
	s_add_u32 s10, s10, 0x20000
	s_addc_u32 s11, s11, 0
	v_lshl_add_u64 v[128:129], v[32:33], 0, s[10:11]
	v_lshl_add_u64 v[130:131], v[30:31], 0, s[10:11]
	v_lshl_add_u64 v[132:133], v[28:29], 0, s[10:11]
	v_lshl_add_u64 v[134:135], v[26:27], 0, s[10:11]
	v_lshl_add_u64 v[136:137], v[24:25], 0, s[10:11]
	v_lshl_add_u64 v[138:139], v[22:23], 0, s[10:11]
	v_lshl_add_u64 v[140:141], v[20:21], 0, s[10:11]
	v_lshl_add_u64 v[142:143], v[18:19], 0, s[10:11]
	global_load_dword v104, v[128:129], off nt
	global_load_dword v105, v[130:131], off nt
	global_load_dword v106, v[132:133], off nt
	global_load_dword v107, v[134:135], off nt
	global_load_dword v108, v[136:137], off nt
	global_load_dword v109, v[138:139], off nt
	global_load_dword v110, v[140:141], off nt
	global_load_dword v111, v[142:143], off nt
	s_add_u32 s10, s10, 0x20000
	s_addc_u32 s11, s11, 0
	v_lshl_add_u64 v[128:129], v[32:33], 0, s[10:11]
	v_lshl_add_u64 v[130:131], v[30:31], 0, s[10:11]
	v_lshl_add_u64 v[132:133], v[28:29], 0, s[10:11]
	v_lshl_add_u64 v[134:135], v[26:27], 0, s[10:11]
	v_lshl_add_u64 v[136:137], v[24:25], 0, s[10:11]
	v_lshl_add_u64 v[138:139], v[22:23], 0, s[10:11]
	v_lshl_add_u64 v[140:141], v[20:21], 0, s[10:11]
	v_lshl_add_u64 v[142:143], v[18:19], 0, s[10:11]
	global_load_dword v112, v[128:129], off nt
	global_load_dword v113, v[130:131], off nt
	global_load_dword v114, v[132:133], off nt
	global_load_dword v115, v[134:135], off nt
	global_load_dword v116, v[136:137], off nt
	global_load_dword v117, v[138:139], off nt
	global_load_dword v118, v[140:141], off nt
	global_load_dword v119, v[142:143], off nt
	s_add_u32 s10, s10, 0x20000
	s_addc_u32 s11, s11, 0
	v_lshl_add_u64 v[128:129], v[32:33], 0, s[10:11]
	v_lshl_add_u64 v[130:131], v[30:31], 0, s[10:11]
	v_lshl_add_u64 v[132:133], v[28:29], 0, s[10:11]
	v_lshl_add_u64 v[134:135], v[26:27], 0, s[10:11]
	v_lshl_add_u64 v[136:137], v[24:25], 0, s[10:11]
	v_lshl_add_u64 v[138:139], v[22:23], 0, s[10:11]
	v_lshl_add_u64 v[140:141], v[20:21], 0, s[10:11]
	v_lshl_add_u64 v[142:143], v[18:19], 0, s[10:11]
	global_load_dword v120, v[128:129], off nt
	global_load_dword v121, v[130:131], off nt
	global_load_dword v122, v[132:133], off nt
	global_load_dword v123, v[134:135], off nt
	global_load_dword v124, v[136:137], off nt
	global_load_dword v125, v[138:139], off nt
	global_load_dword v126, v[140:141], off nt
	global_load_dword v127, v[142:143], off nt
	s_add_u32 s10, s10, 0x20000
	s_addc_u32 s11, s11, 0
	v_add_u32_e32 v65, 0x400, v34
	s_waitcnt vmcnt(30)
	ds_write2_b32 v34, v96, v97 offset1:66
	s_waitcnt vmcnt(28)
	ds_write2_b32 v34, v98, v99 offset0:132 offset1:198
	s_waitcnt vmcnt(26)
	ds_write2_b32 v65, v100, v101 offset0:8 offset1:74
	s_waitcnt vmcnt(24)
	ds_write2_b32 v65, v102, v103 offset0:140 offset1:206
	v_add_u32_e32 v34, 0x840, v34
	v_add_u32_e32 v65, 0x400, v34
	s_waitcnt vmcnt(22)
; #define LAS __attribute__((address_space(3)))
; #define LDS_WAIT() asm volatile("s_waitcnt lgkmcnt(0)" ::: "memory")
; __device__ __forceinline__ unsigned pk2(float lo, float hi) { unsigned r; asm volatile("v_cvt_pk_bf16_f32 %0, %1, %2" : "=v"(r) : "v"(lo), "v"(hi)); return r; }
; __device__ __forceinline__ void p0_transpose_item(const float* W, int ld, int K, int nblk, bf16* WT, LAS float* scr, int item, int lane, bool cumap = false) {
;     ...
;     for (int i = 0; i < 32; ++i) { const int kk = 2 * i + (lane >> 5); scr[kk * 33 + (lane & 31)] = __builtin_nontemporal_load(W + (size_t)(k0 + kk) * ld + n0 + (lane & 31)); }
;     LDS_WAIT(); asm volatile("" ::: "memory");
;     const int c = lane & 7;
; #pragma unroll
;     for (int j = 0; j < 4; ++j) { const int n = (lane >> 3) + 8 * j; const LAS float* s = scr + (8 * c) * 33 + n;
;         v4u o; o.x = pk2(s[0 * 33], s[1 * 33]); o.y = pk2(s[2 * 33], s[3 * 33]); o.z = pk2(s[4 * 33], s[5 * 33]); o.w = pk2(s[6 * 33], s[7 * 33]);
;         *(v4u*)(WT + (size_t)(d0 + n) * K + k0 + 8 * c) = o; }
;     LDS_WAIT(); asm volatile("" ::: "memory");
	ds_write2_b32 v34, v104, v105 offset1:66
	s_waitcnt vmcnt(20)
	ds_write2_b32 v34, v106, v107 offset0:132 offset1:198
	s_waitcnt vmcnt(18)
	ds_write2_b32 v65, v108, v109 offset0:8 offset1:74
	s_waitcnt vmcnt(16)
	ds_write2_b32 v65, v110, v111 offset0:140 offset1:206
	v_add_u32_e32 v34, 0x840, v34
	v_add_u32_e32 v65, 0x400, v34
	s_waitcnt vmcnt(14)
	ds_write2_b32 v34, v112, v113 offset1:66
	s_waitcnt vmcnt(12)
	ds_write2_b32 v34, v114, v115 offset0:132 offset1:198
	s_waitcnt vmcnt(10)
	ds_write2_b32 v65, v116, v117 offset0:8 offset1:74
	s_waitcnt vmcnt(8)
	ds_write2_b32 v65, v118, v119 offset0:140 offset1:206
	v_add_u32_e32 v34, 0x840, v34
	v_add_u32_e32 v65, 0x400, v34
	s_waitcnt vmcnt(6)
	ds_write2_b32 v34, v120, v121 offset1:66
	s_waitcnt vmcnt(4)
	ds_write2_b32 v34, v122, v123 offset0:132 offset1:198
	s_waitcnt vmcnt(2)
	ds_write2_b32 v65, v124, v125 offset0:8 offset1:74
	s_waitcnt vmcnt(0)
	ds_write2_b32 v65, v126, v127 offset0:140 offset1:206
	v_add_u32_e32 v34, 0x840, v34
	s_cmp_lg_u32 s10, 0x80000
	s_waitcnt lgkmcnt(0)
	s_add_i32 s8, s2, 0xc800
	s_lshl_b32 s10, s2, 5
	ds_read2_b32 v[18:19], v38 offset1:33
	s_and_b32 s8, s8, 0xffc0
	s_and_b32 s10, s10, 0x7e0
	s_waitcnt lgkmcnt(0)
	v_cvt_pk_bf16_f32 v18, v18, v19
	ds_read2_b32 v[20:21], v38 offset0:66 offset1:99
	s_lshl_b32 s8, s8, 1
	v_or_b32_e32 v26, s10, v37
	s_waitcnt lgkmcnt(0)
	v_cvt_pk_bf16_f32 v19, v20, v21
	ds_read2_b32 v[20:21], v38 offset0:132 offset1:165
	v_lshl_add_u64 v[24:25], v[8:9], 0, s[8:9]
	v_lshlrev_b32_e32 v194, 12, v26
	s_waitcnt lgkmcnt(0)
	v_cvt_pk_bf16_f32 v20, v20, v21
	ds_read2_b32 v[22:23], v38 offset0:198 offset1:231
	s_waitcnt lgkmcnt(0)
	v_cvt_pk_bf16_f32 v21, v22, v23
	v_lshl_add_u64 v[26:27], v[24:25], 0, v[194:195]
	ds_read2_b32 v[22:23], v38 offset0:8 offset1:41
	global_store_dwordx4 v[26:27], v[18:21], off
	v_or_b32_e32 v26, s10, v39
	v_lshlrev_b32_e32 v194, 12, v26
	s_waitcnt lgkmcnt(0)
	v_cvt_pk_bf16_f32 v18, v22, v23
	ds_read2_b32 v[20:21], v38 offset0:74 offset1:107
	s_waitcnt lgkmcnt(0)
	v_cvt_pk_bf16_f32 v19, v20, v21
	ds_read2_b32 v[20:21], v38 offset0:140 offset1:173
	s_waitcnt lgkmcnt(0)
	v_cvt_pk_bf16_f32 v20, v20, v21
	ds_read2_b32 v[22:23], v38 offset0:206 offset1:239
	s_waitcnt lgkmcnt(0)
	v_cvt_pk_bf16_f32 v21, v22, v23
	v_lshl_add_u64 v[26:27], v[24:25], 0, v[194:195]
	ds_read2_b32 v[22:23], v38 offset0:16 offset1:49
	global_store_dwordx4 v[26:27], v[18:21], off
	v_or_b32_e32 v26, s10, v40
	v_lshlrev_b32_e32 v194, 12, v26
	s_waitcnt lgkmcnt(0)
	v_cvt_pk_bf16_f32 v18, v22, v23
	ds_read2_b32 v[20:21], v38 offset0:82 offset1:115
	s_waitcnt lgkmcnt(0)
	v_cvt_pk_bf16_f32 v19, v20, v21
	ds_read2_b32 v[20:21], v38 offset0:148 offset1:181
	s_waitcnt lgkmcnt(0)
	v_cvt_pk_bf16_f32 v20, v20, v21
	ds_read2_b32 v[22:23], v38 offset0:214 offset1:247
	s_waitcnt lgkmcnt(0)
	v_cvt_pk_bf16_f32 v21, v22, v23
	v_lshl_add_u64 v[26:27], v[24:25], 0, v[194:195]
	ds_read2_b32 v[22:23], v38 offset0:24 offset1:57
	global_store_dwordx4 v[26:27], v[18:21], off
	s_waitcnt lgkmcnt(0)
	s_nop 0
	v_cvt_pk_bf16_f32 v18, v22, v23
	ds_read2_b32 v[20:21], v38 offset0:90 offset1:123
	s_waitcnt lgkmcnt(0)
	v_cvt_pk_bf16_f32 v19, v20, v21
	ds_read2_b32 v[20:21], v38 offset0:156 offset1:189
	s_waitcnt lgkmcnt(0)
	v_cvt_pk_bf16_f32 v20, v20, v21
	v_or_b32_e32 v21, s10, v41
	ds_read2_b32 v[22:23], v38 offset0:222 offset1:255
	v_lshlrev_b32_e32 v194, 12, v21
	s_waitcnt lgkmcnt(0)
	v_cvt_pk_bf16_f32 v21, v22, v23
	v_lshl_add_u64 v[22:23], v[24:25], 0, v[194:195]
	global_store_dwordx4 v[22:23], v[18:21], off
	s_waitcnt lgkmcnt(0)

; __device__ __forceinline__ void p0_transpose_item(const float* W, int ld, int K, int nblk, bf16* WT, LAS float* scr, int item, int lane, bool cumap = false) {
;     ...
; #pragma unroll 8
;     for (int i = 0; i < 32; ++i) { const int kk = 2 * i + (lane >> 5); scr[kk * 33 + (lane & 31)] = __builtin_nontemporal_load(W + (size_t)(k0 + kk) * ld + n0 + (lane & 31)); }
.LBB0_625:
	v_lshl_add_u64 v[128:129], v[32:33], 0, s[10:11]
	v_lshl_add_u64 v[130:131], v[30:31], 0, s[10:11]
	v_lshl_add_u64 v[132:133], v[28:29], 0, s[10:11]
	v_lshl_add_u64 v[134:135], v[26:27], 0, s[10:11]
	v_lshl_add_u64 v[136:137], v[24:25], 0, s[10:11]
	v_lshl_add_u64 v[138:139], v[22:23], 0, s[10:11]
	v_lshl_add_u64 v[140:141], v[20:21], 0, s[10:11]
	v_lshl_add_u64 v[142:143], v[18:19], 0, s[10:11]
	global_load_dword v96, v[128:129], off nt
	global_load_dword v97, v[130:131], off nt
	global_load_dword v98, v[132:133], off nt
	global_load_dword v99, v[134:135], off nt
	global_load_dword v100, v[136:137], off nt
	global_load_dword v101, v[138:139], off nt
	global_load_dword v102, v[140:141], off nt
	global_load_dword v103, v[142:143], off nt
	s_add_u32 s10, s10, 0x60000
	s_addc_u32 s11, s11, 0
	v_lshl_add_u64 v[128:129], v[32:33], 0, s[10:11]
	v_lshl_add_u64 v[130:131], v[30:31], 0, s[10:11]
	v_lshl_add_u64 v[132:133], v[28:29], 0, s[10:11]
	v_lshl_add_u64 v[134:135], v[26:27], 0, s[10:11]
	v_lshl_add_u64 v[136:137], v[24:25], 0, s[10:11]
	v_lshl_add_u64 v[138:139], v[22:23], 0, s[10:11]
	v_lshl_add_u64 v[140:141], v[20:21], 0, s[10:11]
	v_lshl_add_u64 v[142:143], v[18:19], 0, s[10:11]
	global_load_dword v104, v[128:129], off nt
	global_load_dword v105, v[130:131], off nt
	global_load_dword v106, v[132:133], off nt
	global_load_dword v107, v[134:135], off nt
	global_load_dword v108, v[136:137], off nt
	global_load_dword v109, v[138:139], off nt
	global_load_dword v110, v[140:141], off nt
	global_load_dword v111, v[142:143], off nt
	s_add_u32 s10, s10, 0x60000
	s_addc_u32 s11, s11, 0
	v_lshl_add_u64 v[128:129], v[32:33], 0, s[10:11]
	v_lshl_add_u64 v[130:131], v[30:31], 0, s[10:11]
	v_lshl_add_u64 v[132:133], v[28:29], 0, s[10:11]
	v_lshl_add_u64 v[134:135], v[26:27], 0, s[10:11]
	v_lshl_add_u64 v[136:137], v[24:25], 0, s[10:11]
	v_lshl_add_u64 v[138:139], v[22:23], 0, s[10:11]
	v_lshl_add_u64 v[140:141], v[20:21], 0, s[10:11]
	v_lshl_add_u64 v[142:143], v[18:19], 0, s[10:11]
	global_load_dword v112, v[128:129], off nt
	global_load_dword v113, v[130:131], off nt
	global_load_dword v114, v[132:133], off nt
	global_load_dword v115, v[134:135], off nt
	global_load_dword v116, v[136:137], off nt
	global_load_dword v117, v[138:139], off nt
	global_load_dword v118, v[140:141], off nt
	global_load_dword v119, v[142:143], off nt
	s_add_u32 s10, s10, 0x60000
	s_addc_u32 s11, s11, 0
	v_lshl_add_u64 v[128:129], v[32:33], 0, s[10:11]
	v_lshl_add_u64 v[130:131], v[30:31], 0, s[10:11]
	v_lshl_add_u64 v[132:133], v[28:29], 0, s[10:11]
	v_lshl_add_u64 v[134:135], v[26:27], 0, s[10:11]
	v_lshl_add_u64 v[136:137], v[24:25], 0, s[10:11]
	v_lshl_add_u64 v[138:139], v[22:23], 0, s[10:11]
	v_lshl_add_u64 v[140:141], v[20:21], 0, s[10:11]
	v_lshl_add_u64 v[142:143], v[18:19], 0, s[10:11]
	global_load_dword v120, v[128:129], off nt
	global_load_dword v121, v[130:131], off nt
	global_load_dword v122, v[132:133], off nt
	global_load_dword v123, v[134:135], off nt
	global_load_dword v124, v[136:137], off nt
	global_load_dword v125, v[138:139], off nt
	global_load_dword v126, v[140:141], off nt
	global_load_dword v127, v[142:143], off nt
	s_add_u32 s10, s10, 0x60000
	s_addc_u32 s11, s11, 0
	v_add_u32_e32 v65, 0x400, v34
	s_waitcnt vmcnt(30)
	ds_write2_b32 v34, v96, v97 offset1:66
	s_waitcnt vmcnt(28)
	ds_write2_b32 v34, v98, v99 offset0:132 offset1:198
	s_waitcnt vmcnt(26)
	ds_write2_b32 v65, v100, v101 offset0:8 offset1:74
	s_waitcnt vmcnt(24)
; #define LAS __attribute__((address_space(3)))
; #define LDS_WAIT() asm volatile("s_waitcnt lgkmcnt(0)" ::: "memory")
; __device__ __forceinline__ unsigned pk2(float lo, float hi) { unsigned r; asm volatile("v_cvt_pk_bf16_f32 %0, %1, %2" : "=v"(r) : "v"(lo), "v"(hi)); return r; }
; __device__ __forceinline__ void p0_transpose_item(const float* W, int ld, int K, int nblk, bf16* WT, LAS float* scr, int item, int lane, bool cumap = false) {
;     const int kb = item / nblk, nb = item % nblk, k0 = 64 * kb, n0 = 32 * nb;
;     const int d0 = !cumap || n0 < DM ? n0 : (n0 < 2 * DM ? DM + 256 * ((n0 - DM) >> 7) + ((n0 - DM) & 127) : DM + 256 * ((n0 - 2 * DM) >> 7) + 128 + ((n0 - 2 * DM) & 127));
; #pragma unroll 8
;     for (int i = 0; i < 32; ++i) { const int kk = 2 * i + (lane >> 5); scr[kk * 33 + (lane & 31)] = __builtin_nontemporal_load(W + (size_t)(k0 + kk) * ld + n0 + (lane & 31)); }
;     LDS_WAIT(); asm volatile("" ::: "memory");
;     const int c = lane & 7;
; #pragma unroll
;     for (int j = 0; j < 4; ++j) { const int n = (lane >> 3) + 8 * j; const LAS float* s = scr + (8 * c) * 33 + n;
;         v4u o; o.x = pk2(s[0 * 33], s[1 * 33]); o.y = pk2(s[2 * 33], s[3 * 33]); o.z = pk2(s[4 * 33], s[5 * 33]); o.w = pk2(s[6 * 33], s[7 * 33]);
;         *(v4u*)(WT + (size_t)(d0 + n) * K + k0 + 8 * c) = o; }
;     LDS_WAIT(); asm volatile("" ::: "memory");
	ds_write2_b32 v65, v102, v103 offset0:140 offset1:206
	v_add_u32_e32 v34, 0x840, v34
	v_add_u32_e32 v65, 0x400, v34
	s_waitcnt vmcnt(22)
	ds_write2_b32 v34, v104, v105 offset1:66
	s_waitcnt vmcnt(20)
	ds_write2_b32 v34, v106, v107 offset0:132 offset1:198
	s_waitcnt vmcnt(18)
	ds_write2_b32 v65, v108, v109 offset0:8 offset1:74
	s_waitcnt vmcnt(16)
	ds_write2_b32 v65, v110, v111 offset0:140 offset1:206
	v_add_u32_e32 v34, 0x840, v34
	v_add_u32_e32 v65, 0x400, v34
	s_waitcnt vmcnt(14)
	ds_write2_b32 v34, v112, v113 offset1:66
	s_waitcnt vmcnt(12)
	ds_write2_b32 v34, v114, v115 offset0:132 offset1:198
	s_waitcnt vmcnt(10)
	ds_write2_b32 v65, v116, v117 offset0:8 offset1:74
	s_waitcnt vmcnt(8)
	ds_write2_b32 v65, v118, v119 offset0:140 offset1:206
	v_add_u32_e32 v34, 0x840, v34
	v_add_u32_e32 v65, 0x400, v34
	s_waitcnt vmcnt(6)
	ds_write2_b32 v34, v120, v121 offset1:66
	s_waitcnt vmcnt(4)
	ds_write2_b32 v34, v122, v123 offset0:132 offset1:198
	s_waitcnt vmcnt(2)
	ds_write2_b32 v65, v124, v125 offset0:8 offset1:74
	s_waitcnt vmcnt(0)
	ds_write2_b32 v65, v126, v127 offset0:140 offset1:206
	v_add_u32_e32 v34, 0x840, v34
	s_cmp_lg_u32 s10, 0x180000
	s_waitcnt lgkmcnt(0)
	ds_read2_b32 v[18:19], v38 offset1:33
	s_waitcnt lgkmcnt(0)
	v_cvt_pk_bf16_f32 v18, v18, v19
	ds_read2_b32 v[20:21], v38 offset0:66 offset1:99
	s_lshl_b32 s8, s16, 1
	v_add_u32_e32 v194, s15, v37
	s_waitcnt lgkmcnt(0)
	v_cvt_pk_bf16_f32 v19, v20, v21
	ds_read2_b32 v[20:21], v38 offset0:132 offset1:165
	v_lshl_add_u64 v[24:25], v[10:11], 0, s[8:9]
	v_lshlrev_b64 v[26:27], 12, v[194:195]
	s_waitcnt lgkmcnt(0)
	v_cvt_pk_bf16_f32 v20, v20, v21
	ds_read2_b32 v[22:23], v38 offset0:198 offset1:231
	s_waitcnt lgkmcnt(0)
	v_cvt_pk_bf16_f32 v21, v22, v23
	v_lshl_add_u64 v[26:27], v[24:25], 0, v[26:27]
	ds_read2_b32 v[22:23], v38 offset0:8 offset1:41
	global_store_dwordx4 v[26:27], v[18:21], off
	v_add_u32_e32 v194, s15, v39
	v_lshlrev_b64 v[26:27], 12, v[194:195]
	s_waitcnt lgkmcnt(0)
	v_cvt_pk_bf16_f32 v18, v22, v23
	ds_read2_b32 v[20:21], v38 offset0:74 offset1:107
	s_waitcnt lgkmcnt(0)
	v_cvt_pk_bf16_f32 v19, v20, v21
	ds_read2_b32 v[20:21], v38 offset0:140 offset1:173
	s_waitcnt lgkmcnt(0)
	v_cvt_pk_bf16_f32 v20, v20, v21
	ds_read2_b32 v[22:23], v38 offset0:206 offset1:239
	s_waitcnt lgkmcnt(0)
	v_cvt_pk_bf16_f32 v21, v22, v23
	v_lshl_add_u64 v[26:27], v[24:25], 0, v[26:27]
	ds_read2_b32 v[22:23], v38 offset0:16 offset1:49
	global_store_dwordx4 v[26:27], v[18:21], off
	v_add_u32_e32 v194, s15, v40
	v_lshlrev_b64 v[26:27], 12, v[194:195]
	s_waitcnt lgkmcnt(0)
	v_cvt_pk_bf16_f32 v18, v22, v23
	ds_read2_b32 v[20:21], v38 offset0:82 offset1:115
	s_waitcnt lgkmcnt(0)
	v_cvt_pk_bf16_f32 v19, v20, v21
	ds_read2_b32 v[20:21], v38 offset0:148 offset1:181
	s_waitcnt lgkmcnt(0)
	v_cvt_pk_bf16_f32 v20, v20, v21
	ds_read2_b32 v[22:23], v38 offset0:214 offset1:247
	s_waitcnt lgkmcnt(0)
	v_cvt_pk_bf16_f32 v21, v22, v23
	v_lshl_add_u64 v[26:27], v[24:25], 0, v[26:27]
	ds_read2_b32 v[22:23], v38 offset0:24 offset1:57
	global_store_dwordx4 v[26:27], v[18:21], off
	v_add_u32_e32 v194, s15, v41
	v_lshlrev_b64 v[26:27], 12, v[194:195]
	s_waitcnt lgkmcnt(0)
	v_cvt_pk_bf16_f32 v18, v22, v23
	ds_read2_b32 v[20:21], v38 offset0:90 offset1:123
	s_waitcnt lgkmcnt(0)
	v_cvt_pk_bf16_f32 v19, v20, v21
	ds_read2_b32 v[20:21], v38 offset0:156 offset1:189
	s_waitcnt lgkmcnt(0)
	v_cvt_pk_bf16_f32 v20, v20, v21
	ds_read2_b32 v[22:23], v38 offset0:222 offset1:255
	s_waitcnt lgkmcnt(0)
	v_cvt_pk_bf16_f32 v21, v22, v23
	v_lshl_add_u64 v[22:23], v[24:25], 0, v[26:27]
	global_store_dwordx4 v[22:23], v[18:21], off
	s_waitcnt lgkmcnt(0)

; __device__ __forceinline__ void p0_transpose_item(const float* W, int ld, int K, int nblk, bf16* WT, LAS float* scr, int item, int lane, bool cumap = false) {
;     ...
; #pragma unroll 8
;     for (int i = 0; i < 32; ++i) { const int kk = 2 * i + (lane >> 5); scr[kk * 33 + (lane & 31)] = __builtin_nontemporal_load(W + (size_t)(k0 + kk) * ld + n0 + (lane & 31)); }
.LBB0_630:
	v_lshl_add_u64 v[128:129], v[32:33], 0, s[10:11]
	v_lshl_add_u64 v[130:131], v[30:31], 0, s[10:11]
	v_lshl_add_u64 v[132:133], v[28:29], 0, s[10:11]
	v_lshl_add_u64 v[134:135], v[26:27], 0, s[10:11]
	v_lshl_add_u64 v[136:137], v[24:25], 0, s[10:11]
	v_lshl_add_u64 v[138:139], v[22:23], 0, s[10:11]
	v_lshl_add_u64 v[140:141], v[20:21], 0, s[10:11]
	v_lshl_add_u64 v[142:143], v[18:19], 0, s[10:11]
	global_load_dword v96, v[128:129], off nt
	global_load_dword v97, v[130:131], off nt
	global_load_dword v98, v[132:133], off nt
	global_load_dword v99, v[134:135], off nt
	global_load_dword v100, v[136:137], off nt
	global_load_dword v101, v[138:139], off nt
	global_load_dword v102, v[140:141], off nt
	global_load_dword v103, v[142:143], off nt
	s_add_u32 s10, s10, 0x20000
	s_addc_u32 s11, s11, 0
	v_lshl_add_u64 v[128:129], v[32:33], 0, s[10:11]
	v_lshl_add_u64 v[130:131], v[30:31], 0, s[10:11]
	v_lshl_add_u64 v[132:133], v[28:29], 0, s[10:11]
	v_lshl_add_u64 v[134:135], v[26:27], 0, s[10:11]
	v_lshl_add_u64 v[136:137], v[24:25], 0, s[10:11]
	v_lshl_add_u64 v[138:139], v[22:23], 0, s[10:11]
	v_lshl_add_u64 v[140:141], v[20:21], 0, s[10:11]
	v_lshl_add_u64 v[142:143], v[18:19], 0, s[10:11]
	global_load_dword v104, v[128:129], off nt
	global_load_dword v105, v[130:131], off nt
	global_load_dword v106, v[132:133], off nt
	global_load_dword v107, v[134:135], off nt
	global_load_dword v108, v[136:137], off nt
	global_load_dword v109, v[138:139], off nt
	global_load_dword v110, v[140:141], off nt
	global_load_dword v111, v[142:143], off nt
	s_add_u32 s10, s10, 0x20000
	s_addc_u32 s11, s11, 0
	v_lshl_add_u64 v[128:129], v[32:33], 0, s[10:11]
	v_lshl_add_u64 v[130:131], v[30:31], 0, s[10:11]
	v_lshl_add_u64 v[132:133], v[28:29], 0, s[10:11]
	v_lshl_add_u64 v[134:135], v[26:27], 0, s[10:11]
	v_lshl_add_u64 v[136:137], v[24:25], 0, s[10:11]
	v_lshl_add_u64 v[138:139], v[22:23], 0, s[10:11]
	v_lshl_add_u64 v[140:141], v[20:21], 0, s[10:11]
	v_lshl_add_u64 v[142:143], v[18:19], 0, s[10:11]
	global_load_dword v112, v[128:129], off nt
	global_load_dword v113, v[130:131], off nt
	global_load_dword v114, v[132:133], off nt
	global_load_dword v115, v[134:135], off nt
	global_load_dword v116, v[136:137], off nt
	global_load_dword v117, v[138:139], off nt
	global_load_dword v118, v[140:141], off nt
	global_load_dword v119, v[142:143], off nt
	s_add_u32 s10, s10, 0x20000
	s_addc_u32 s11, s11, 0
	v_lshl_add_u64 v[128:129], v[32:33], 0, s[10:11]
	v_lshl_add_u64 v[130:131], v[30:31], 0, s[10:11]
	v_lshl_add_u64 v[132:133], v[28:29], 0, s[10:11]
	v_lshl_add_u64 v[134:135], v[26:27], 0, s[10:11]
	v_lshl_add_u64 v[136:137], v[24:25], 0, s[10:11]
	v_lshl_add_u64 v[138:139], v[22:23], 0, s[10:11]
	v_lshl_add_u64 v[140:141], v[20:21], 0, s[10:11]
	v_lshl_add_u64 v[142:143], v[18:19], 0, s[10:11]
	global_load_dword v120, v[128:129], off nt
	global_load_dword v121, v[130:131], off nt
	global_load_dword v122, v[132:133], off nt
	global_load_dword v123, v[134:135], off nt
	global_load_dword v124, v[136:137], off nt
	global_load_dword v125, v[138:139], off nt
	global_load_dword v126, v[140:141], off nt
	global_load_dword v127, v[142:143], off nt
	s_add_u32 s10, s10, 0x20000
	s_addc_u32 s11, s11, 0
	v_add_u32_e32 v65, 0x400, v34
	s_waitcnt vmcnt(30)
	ds_write2_b32 v34, v96, v97 offset1:66
	s_waitcnt vmcnt(28)
	ds_write2_b32 v34, v98, v99 offset0:132 offset1:198
	s_waitcnt vmcnt(26)
	ds_write2_b32 v65, v100, v101 offset0:8 offset1:74
	s_waitcnt vmcnt(24)
	ds_write2_b32 v65, v102, v103 offset0:140 offset1:206
	v_add_u32_e32 v34, 0x840, v34
	v_add_u32_e32 v65, 0x400, v34
	s_waitcnt vmcnt(22)
; #define LAS __attribute__((address_space(3)))
; #define LDS_WAIT() asm volatile("s_waitcnt lgkmcnt(0)" ::: "memory")
; __device__ __forceinline__ unsigned pk2(float lo, float hi) { unsigned r; asm volatile("v_cvt_pk_bf16_f32 %0, %1, %2" : "=v"(r) : "v"(lo), "v"(hi)); return r; }
; __device__ __forceinline__ void p0_transpose_item(const float* W, int ld, int K, int nblk, bf16* WT, LAS float* scr, int item, int lane, bool cumap = false) {
;     ...
;     for (int i = 0; i < 32; ++i) { const int kk = 2 * i + (lane >> 5); scr[kk * 33 + (lane & 31)] = __builtin_nontemporal_load(W + (size_t)(k0 + kk) * ld + n0 + (lane & 31)); }
;     LDS_WAIT(); asm volatile("" ::: "memory");
;     const int c = lane & 7;
; #pragma unroll
;     for (int j = 0; j < 4; ++j) { const int n = (lane >> 3) + 8 * j; const LAS float* s = scr + (8 * c) * 33 + n;
;         v4u o; o.x = pk2(s[0 * 33], s[1 * 33]); o.y = pk2(s[2 * 33], s[3 * 33]); o.z = pk2(s[4 * 33], s[5 * 33]); o.w = pk2(s[6 * 33], s[7 * 33]);
;         *(v4u*)(WT + (size_t)(d0 + n) * K + k0 + 8 * c) = o; }
;     LDS_WAIT(); asm volatile("" ::: "memory");
	ds_write2_b32 v34, v104, v105 offset1:66
	s_waitcnt vmcnt(20)
	ds_write2_b32 v34, v106, v107 offset0:132 offset1:198
	s_waitcnt vmcnt(18)
	ds_write2_b32 v65, v108, v109 offset0:8 offset1:74
	s_waitcnt vmcnt(16)
	ds_write2_b32 v65, v110, v111 offset0:140 offset1:206
	v_add_u32_e32 v34, 0x840, v34
	v_add_u32_e32 v65, 0x400, v34
	s_waitcnt vmcnt(14)
	ds_write2_b32 v34, v112, v113 offset1:66
	s_waitcnt vmcnt(12)
	ds_write2_b32 v34, v114, v115 offset0:132 offset1:198
	s_waitcnt vmcnt(10)
	ds_write2_b32 v65, v116, v117 offset0:8 offset1:74
	s_waitcnt vmcnt(8)
	ds_write2_b32 v65, v118, v119 offset0:140 offset1:206
	v_add_u32_e32 v34, 0x840, v34
	v_add_u32_e32 v65, 0x400, v34
	s_waitcnt vmcnt(6)
	ds_write2_b32 v34, v120, v121 offset1:66
	s_waitcnt vmcnt(4)
	ds_write2_b32 v34, v122, v123 offset0:132 offset1:198
	s_waitcnt vmcnt(2)
	ds_write2_b32 v65, v124, v125 offset0:8 offset1:74
	s_waitcnt vmcnt(0)
	ds_write2_b32 v65, v126, v127 offset0:140 offset1:206
	v_add_u32_e32 v34, 0x840, v34
	s_cmp_lg_u32 s10, 0x80000
	s_waitcnt lgkmcnt(0)
	s_add_i32 s8, s2, 0xe800
	s_lshl_b32 s10, s2, 5
	ds_read2_b32 v[18:19], v38 offset1:33
	s_and_b32 s8, s8, 0xffc0
	s_and_b32 s10, s10, 0x7e0
	s_waitcnt lgkmcnt(0)
	v_cvt_pk_bf16_f32 v18, v18, v19
	ds_read2_b32 v[20:21], v38 offset0:66 offset1:99
	s_lshl_b32 s8, s8, 1
	v_or_b32_e32 v26, s10, v37
	s_waitcnt lgkmcnt(0)
	v_cvt_pk_bf16_f32 v19, v20, v21
	ds_read2_b32 v[20:21], v38 offset0:132 offset1:165
	v_lshl_add_u64 v[24:25], v[12:13], 0, s[8:9]
	v_lshlrev_b32_e32 v194, 12, v26
	s_waitcnt lgkmcnt(0)
	v_cvt_pk_bf16_f32 v20, v20, v21
	ds_read2_b32 v[22:23], v38 offset0:198 offset1:231
	s_waitcnt lgkmcnt(0)
	v_cvt_pk_bf16_f32 v21, v22, v23
	v_lshl_add_u64 v[26:27], v[24:25], 0, v[194:195]
	ds_read2_b32 v[22:23], v38 offset0:8 offset1:41
	global_store_dwordx4 v[26:27], v[18:21], off
	v_or_b32_e32 v26, s10, v39
	v_lshlrev_b32_e32 v194, 12, v26
	s_waitcnt lgkmcnt(0)
	v_cvt_pk_bf16_f32 v18, v22, v23
	ds_read2_b32 v[20:21], v38 offset0:74 offset1:107
	s_waitcnt lgkmcnt(0)
	v_cvt_pk_bf16_f32 v19, v20, v21
	ds_read2_b32 v[20:21], v38 offset0:140 offset1:173
	s_waitcnt lgkmcnt(0)
	v_cvt_pk_bf16_f32 v20, v20, v21
	ds_read2_b32 v[22:23], v38 offset0:206 offset1:239
	s_waitcnt lgkmcnt(0)
	v_cvt_pk_bf16_f32 v21, v22, v23
	v_lshl_add_u64 v[26:27], v[24:25], 0, v[194:195]
	ds_read2_b32 v[22:23], v38 offset0:16 offset1:49
	global_store_dwordx4 v[26:27], v[18:21], off
	v_or_b32_e32 v26, s10, v40
	v_lshlrev_b32_e32 v194, 12, v26
	s_waitcnt lgkmcnt(0)
	v_cvt_pk_bf16_f32 v18, v22, v23
	ds_read2_b32 v[20:21], v38 offset0:82 offset1:115
	s_waitcnt lgkmcnt(0)
	v_cvt_pk_bf16_f32 v19, v20, v21
	ds_read2_b32 v[20:21], v38 offset0:148 offset1:181
	s_waitcnt lgkmcnt(0)
	v_cvt_pk_bf16_f32 v20, v20, v21
	ds_read2_b32 v[22:23], v38 offset0:214 offset1:247
	s_waitcnt lgkmcnt(0)
	v_cvt_pk_bf16_f32 v21, v22, v23
	v_lshl_add_u64 v[26:27], v[24:25], 0, v[194:195]
	ds_read2_b32 v[22:23], v38 offset0:24 offset1:57
	global_store_dwordx4 v[26:27], v[18:21], off
	s_waitcnt lgkmcnt(0)
	s_nop 0
	v_cvt_pk_bf16_f32 v18, v22, v23
	ds_read2_b32 v[20:21], v38 offset0:90 offset1:123
	s_waitcnt lgkmcnt(0)
	v_cvt_pk_bf16_f32 v19, v20, v21
	ds_read2_b32 v[20:21], v38 offset0:156 offset1:189
	s_waitcnt lgkmcnt(0)
	v_cvt_pk_bf16_f32 v20, v20, v21
	v_or_b32_e32 v21, s10, v41
	ds_read2_b32 v[22:23], v38 offset0:222 offset1:255
	v_lshlrev_b32_e32 v194, 12, v21
	s_waitcnt lgkmcnt(0)
	v_cvt_pk_bf16_f32 v21, v22, v23
	v_lshl_add_u64 v[22:23], v[24:25], 0, v[194:195]
	global_store_dwordx4 v[22:23], v[18:21], off
	s_waitcnt lgkmcnt(0)

; #define KARG_IN(kq, i) (*(const float* const __attribute__((address_space(4)))*)((kq) + 8 * (i)))
; __device__ __forceinline__ void p0_transpose_item(const float* W, int ld, int K, int nblk, bf16* WT, LAS float* scr, int item, int lane, bool cumap = false) {
;     ...
; #pragma unroll 8
;     for (int i = 0; i < 32; ++i) { const int kk = 2 * i + (lane >> 5); scr[kk * 33 + (lane & 31)] = __builtin_nontemporal_load(W + (size_t)(k0 + kk) * ld + n0 + (lane & 31)); }
; __device__ __forceinline__ void p0_transposes(kargp_t kq, LAS unsigned char* lds, int wave, int lane, int gw, int ngw) {
;     ...
;         if (r < I_IN) { p0_transpose_item(KARG_IN(kq, 6), NIN, DM, 192, (bf16*)(ws + WS_WQKV), scr, r, lane); continue; } r -= I_IN;
.LBB0_635:
	v_lshl_add_u64 v[128:129], v[32:33], 0, s[16:17]
	v_lshl_add_u64 v[130:131], v[30:31], 0, s[16:17]
	v_lshl_add_u64 v[132:133], v[28:29], 0, s[16:17]
	v_lshl_add_u64 v[134:135], v[26:27], 0, s[16:17]
	v_lshl_add_u64 v[136:137], v[24:25], 0, s[16:17]
	v_lshl_add_u64 v[138:139], v[22:23], 0, s[16:17]
	v_lshl_add_u64 v[140:141], v[20:21], 0, s[16:17]
	v_lshl_add_u64 v[142:143], v[18:19], 0, s[16:17]
	global_load_dword v96, v[128:129], off nt
	global_load_dword v97, v[130:131], off nt
	global_load_dword v98, v[132:133], off nt
	global_load_dword v99, v[134:135], off nt
	global_load_dword v100, v[136:137], off nt
	global_load_dword v101, v[138:139], off nt
	global_load_dword v102, v[140:141], off nt
	global_load_dword v103, v[142:143], off nt
	s_add_u32 s16, s16, 0x60400
	s_addc_u32 s17, s17, 0
	v_lshl_add_u64 v[128:129], v[32:33], 0, s[16:17]
	v_lshl_add_u64 v[130:131], v[30:31], 0, s[16:17]
	v_lshl_add_u64 v[132:133], v[28:29], 0, s[16:17]
	v_lshl_add_u64 v[134:135], v[26:27], 0, s[16:17]
	v_lshl_add_u64 v[136:137], v[24:25], 0, s[16:17]
	v_lshl_add_u64 v[138:139], v[22:23], 0, s[16:17]
	v_lshl_add_u64 v[140:141], v[20:21], 0, s[16:17]
	v_lshl_add_u64 v[142:143], v[18:19], 0, s[16:17]
	global_load_dword v104, v[128:129], off nt
	global_load_dword v105, v[130:131], off nt
	global_load_dword v106, v[132:133], off nt
	global_load_dword v107, v[134:135], off nt
	global_load_dword v108, v[136:137], off nt
	global_load_dword v109, v[138:139], off nt
	global_load_dword v110, v[140:141], off nt
	global_load_dword v111, v[142:143], off nt
	s_add_u32 s16, s16, 0x60400
	s_addc_u32 s17, s17, 0
	v_lshl_add_u64 v[128:129], v[32:33], 0, s[16:17]
	v_lshl_add_u64 v[130:131], v[30:31], 0, s[16:17]
	v_lshl_add_u64 v[132:133], v[28:29], 0, s[16:17]
	v_lshl_add_u64 v[134:135], v[26:27], 0, s[16:17]
	v_lshl_add_u64 v[136:137], v[24:25], 0, s[16:17]
	v_lshl_add_u64 v[138:139], v[22:23], 0, s[16:17]
	v_lshl_add_u64 v[140:141], v[20:21], 0, s[16:17]
	v_lshl_add_u64 v[142:143], v[18:19], 0, s[16:17]
	global_load_dword v112, v[128:129], off nt
	global_load_dword v113, v[130:131], off nt
	global_load_dword v114, v[132:133], off nt
	global_load_dword v115, v[134:135], off nt
	global_load_dword v116, v[136:137], off nt
	global_load_dword v117, v[138:139], off nt
	global_load_dword v118, v[140:141], off nt
	global_load_dword v119, v[142:143], off nt
	s_add_u32 s16, s16, 0x60400
	s_addc_u32 s17, s17, 0
	v_lshl_add_u64 v[128:129], v[32:33], 0, s[16:17]
	v_lshl_add_u64 v[130:131], v[30:31], 0, s[16:17]
	v_lshl_add_u64 v[132:133], v[28:29], 0, s[16:17]
	v_lshl_add_u64 v[134:135], v[26:27], 0, s[16:17]
	v_lshl_add_u64 v[136:137], v[24:25], 0, s[16:17]
	v_lshl_add_u64 v[138:139], v[22:23], 0, s[16:17]
	v_lshl_add_u64 v[140:141], v[20:21], 0, s[16:17]
	v_lshl_add_u64 v[142:143], v[18:19], 0, s[16:17]
	global_load_dword v120, v[128:129], off nt
	global_load_dword v121, v[130:131], off nt
	global_load_dword v122, v[132:133], off nt
	global_load_dword v123, v[134:135], off nt
	global_load_dword v124, v[136:137], off nt
	global_load_dword v125, v[138:139], off nt
	global_load_dword v126, v[140:141], off nt
	global_load_dword v127, v[142:143], off nt
	s_add_u32 s16, s16, 0x60400
	s_addc_u32 s17, s17, 0
	v_add_u32_e32 v65, 0x400, v34
	s_waitcnt vmcnt(30)
	ds_write2_b32 v34, v96, v97 offset1:66
	s_waitcnt vmcnt(28)
	ds_write2_b32 v34, v98, v99 offset0:132 offset1:198
	s_waitcnt vmcnt(26)
	ds_write2_b32 v65, v100, v101 offset0:8 offset1:74
	s_waitcnt vmcnt(24)
	ds_write2_b32 v65, v102, v103 offset0:140 offset1:206
	v_add_u32_e32 v34, 0x840, v34
	v_add_u32_e32 v65, 0x400, v34
	s_waitcnt vmcnt(22)
; #define LAS __attribute__((address_space(3)))
; #define LDS_WAIT() asm volatile("s_waitcnt lgkmcnt(0)" ::: "memory")
; __device__ __forceinline__ unsigned pk2(float lo, float hi) { unsigned r; asm volatile("v_cvt_pk_bf16_f32 %0, %1, %2" : "=v"(r) : "v"(lo), "v"(hi)); return r; }
; __device__ __forceinline__ void p0_transpose_item(const float* W, int ld, int K, int nblk, bf16* WT, LAS float* scr, int item, int lane, bool cumap = false) {
;     ...
;     for (int i = 0; i < 32; ++i) { const int kk = 2 * i + (lane >> 5); scr[kk * 33 + (lane & 31)] = __builtin_nontemporal_load(W + (size_t)(k0 + kk) * ld + n0 + (lane & 31)); }
;     LDS_WAIT(); asm volatile("" ::: "memory");
;     const int c = lane & 7;
; #pragma unroll
;     for (int j = 0; j < 4; ++j) { const int n = (lane >> 3) + 8 * j; const LAS float* s = scr + (8 * c) * 33 + n;
;         v4u o; o.x = pk2(s[0 * 33], s[1 * 33]); o.y = pk2(s[2 * 33], s[3 * 33]); o.z = pk2(s[4 * 33], s[5 * 33]); o.w = pk2(s[6 * 33], s[7 * 33]);
;         *(v4u*)(WT + (size_t)(d0 + n) * K + k0 + 8 * c) = o; }
;     LDS_WAIT(); asm volatile("" ::: "memory");
; __device__ __forceinline__ void p0_transposes(kargp_t kq, LAS unsigned char* lds, int wave, int lane, int gw, int ngw) {
;     ...
;     for (int it = first; it < stop; it += step) {
	ds_write2_b32 v34, v104, v105 offset1:66
	s_waitcnt vmcnt(20)
	ds_write2_b32 v34, v106, v107 offset0:132 offset1:198
	s_waitcnt vmcnt(18)
	ds_write2_b32 v65, v108, v109 offset0:8 offset1:74
	s_waitcnt vmcnt(16)
	ds_write2_b32 v65, v110, v111 offset0:140 offset1:206
	v_add_u32_e32 v34, 0x840, v34
	v_add_u32_e32 v65, 0x400, v34
	s_waitcnt vmcnt(14)
	ds_write2_b32 v34, v112, v113 offset1:66
	s_waitcnt vmcnt(12)
	ds_write2_b32 v34, v114, v115 offset0:132 offset1:198
	s_waitcnt vmcnt(10)
	ds_write2_b32 v65, v116, v117 offset0:8 offset1:74
	s_waitcnt vmcnt(8)
	ds_write2_b32 v65, v118, v119 offset0:140 offset1:206
	v_add_u32_e32 v34, 0x840, v34
	v_add_u32_e32 v65, 0x400, v34
	s_waitcnt vmcnt(6)
	ds_write2_b32 v34, v120, v121 offset1:66
	s_waitcnt vmcnt(4)
	ds_write2_b32 v34, v122, v123 offset0:132 offset1:198
	s_waitcnt vmcnt(2)
	ds_write2_b32 v65, v124, v125 offset0:8 offset1:74
	s_waitcnt vmcnt(0)
	ds_write2_b32 v65, v126, v127 offset0:140 offset1:206
	v_add_u32_e32 v34, 0x840, v34
	s_cmp_lg_u32 s16, 0x181000
	s_waitcnt lgkmcnt(0)
	v_or_b32_e32 v24, s10, v37
	ds_read2_b32 v[18:19], v38 offset1:33
	s_ashr_i32 s15, s14, 31
	v_ashrrev_i32_e32 v25, 31, v24
	s_waitcnt lgkmcnt(0)
	v_cvt_pk_bf16_f32 v18, v18, v19
	ds_read2_b32 v[20:21], v38 offset0:66 offset1:99
	v_lshl_add_u64 v[26:27], s[14:15], 1, v[14:15]
	v_lshlrev_b64 v[24:25], 12, v[24:25]
	s_waitcnt lgkmcnt(0)
	v_cvt_pk_bf16_f32 v19, v20, v21
	ds_read2_b32 v[20:21], v38 offset0:132 offset1:165
	v_lshl_add_u64 v[24:25], v[26:27], 0, v[24:25]
	s_waitcnt lgkmcnt(0)
	v_cvt_pk_bf16_f32 v20, v20, v21
	ds_read2_b32 v[22:23], v38 offset0:198 offset1:231
	s_waitcnt lgkmcnt(0)
	v_cvt_pk_bf16_f32 v21, v22, v23
	global_store_dwordx4 v[24:25], v[18:21], off
	v_or_b32_e32 v24, s10, v39
	v_ashrrev_i32_e32 v25, 31, v24
	ds_read2_b32 v[22:23], v38 offset0:8 offset1:41
	s_waitcnt lgkmcnt(0)
	v_cvt_pk_bf16_f32 v18, v22, v23
	ds_read2_b32 v[20:21], v38 offset0:74 offset1:107
	v_lshlrev_b64 v[24:25], 12, v[24:25]
	s_waitcnt lgkmcnt(0)
	v_cvt_pk_bf16_f32 v19, v20, v21
	ds_read2_b32 v[20:21], v38 offset0:140 offset1:173
	v_lshl_add_u64 v[24:25], v[26:27], 0, v[24:25]
	s_waitcnt lgkmcnt(0)
	v_cvt_pk_bf16_f32 v20, v20, v21
	ds_read2_b32 v[22:23], v38 offset0:206 offset1:239
	s_waitcnt lgkmcnt(0)
	v_cvt_pk_bf16_f32 v21, v22, v23
	global_store_dwordx4 v[24:25], v[18:21], off
	v_or_b32_e32 v24, s10, v40
	ds_read2_b32 v[22:23], v38 offset0:16 offset1:49
	s_waitcnt lgkmcnt(0)
	v_cvt_pk_bf16_f32 v18, v22, v23
	ds_read2_b32 v[20:21], v38 offset0:82 offset1:115
	v_ashrrev_i32_e32 v25, 31, v24
	s_waitcnt lgkmcnt(0)
	v_cvt_pk_bf16_f32 v19, v20, v21
	ds_read2_b32 v[20:21], v38 offset0:148 offset1:181
	v_lshlrev_b64 v[24:25], 12, v[24:25]
	s_waitcnt lgkmcnt(0)
	v_cvt_pk_bf16_f32 v20, v20, v21
	ds_read2_b32 v[22:23], v38 offset0:214 offset1:247
	s_waitcnt lgkmcnt(0)
	v_cvt_pk_bf16_f32 v21, v22, v23
	v_lshl_add_u64 v[24:25], v[26:27], 0, v[24:25]
	ds_read2_b32 v[22:23], v38 offset0:24 offset1:57
	global_store_dwordx4 v[24:25], v[18:21], off
	v_or_b32_e32 v24, s10, v41
	v_ashrrev_i32_e32 v25, 31, v24
	s_waitcnt lgkmcnt(0)
	v_cvt_pk_bf16_f32 v18, v22, v23
	ds_read2_b32 v[20:21], v38 offset0:90 offset1:123
	s_waitcnt lgkmcnt(0)
	v_cvt_pk_bf16_f32 v19, v20, v21
	ds_read2_b32 v[20:21], v38 offset0:156 offset1:189
	s_waitcnt lgkmcnt(0)
	v_cvt_pk_bf16_f32 v20, v20, v21
	ds_read2_b32 v[22:23], v38 offset0:222 offset1:255
	v_lshlrev_b64 v[24:25], 12, v[24:25]
	s_waitcnt lgkmcnt(0)
	v_cvt_pk_bf16_f32 v21, v22, v23
	v_lshl_add_u64 v[22:23], v[26:27], 0, v[24:25]
	global_store_dwordx4 v[22:23], v[18:21], off
	s_waitcnt lgkmcnt(0)
	s_branch .LBB0_587
